# pipelined coalesced stores in E/POOL/PLE/gelu/YA/YB epilogues with counted vmcnt waits adjusted for the one delayed store
# speedup vs baseline: 1.0009x; 1.0009x over previous
; __device__ __forceinline__ unsigned cvt_pk_bf16(float lo, float hi) { f32x2 v = {lo, hi}; bf16x2_t b = __builtin_convertvector(v, bf16x2_t); return __builtin_bit_cast(unsigned, b); }
; __device__ __forceinline__ float bf_lo(unsigned w) { return __uint_as_float(w << 16); }
; __device__ __forceinline__ float bf_hi(unsigned w) { return __uint_as_float(w & 0xffff0000u); }
; __device__ __forceinline__ float sigm(float v) { return __builtin_amdgcn_rcpf(1.0f + __builtin_amdgcn_exp2f(-1.44269504089f * v)); }
; #define EPI_FENCE asm volatile("" ::: "memory")
; __device__ __forceinline__ void epi_run(const Epi& E, f32x4 (&acc)[2][2][4][2], const Unit& u, int wr, int wc, int fr, int fq) {
;     ...
;     } else if (mode == MODE_YB) {
; #pragma unroll
;         for (int ai = 0; ai < 2; ++ai) { u32x4 g[4][2], c[4][2];
; #pragma unroll
;             for (int m = 0; m < 4; ++m)
; #pragma unroll
;                 for (int bj = 0; bj < 2; ++bj) { const bf16_t* gp = E.Z + (size_t)(row0 + ai * 128 + m * 16) * NIN + 4096 + col0 + bj * 128; g[m][bj] = *(const u32x4*)gp; c[m][bj] = *(const u32x4*)(gp - 1024); }
; #pragma unroll
;             for (int m = 0; m < 4; ++m)
; #pragma unroll
;                 for (int bj = 0; bj < 2; ++bj) { const f32x4 v0 = acc[ai][bj][m][0], v1 = acc[ai][bj][m][1]; const u32x4 gg = g[m][bj], cc = c[m][bj]; u32x4 w;
;                     w.x = cvt_pk_bf16(bf_lo(cc.x) + v0[0] * sigm(bf_lo(gg.x)), bf_hi(cc.x) + v0[1] * sigm(bf_hi(gg.x))); w.y = cvt_pk_bf16(bf_lo(cc.y) + v0[2] * sigm(bf_lo(gg.y)), bf_hi(cc.y) + v0[3] * sigm(bf_hi(gg.y)));
;                     w.z = cvt_pk_bf16(bf_lo(cc.z) + v1[0] * sigm(bf_lo(gg.z)), bf_hi(cc.z) + v1[1] * sigm(bf_hi(gg.z))); w.w = cvt_pk_bf16(bf_lo(cc.w) + v1[2] * sigm(bf_lo(gg.w)), bf_hi(cc.w) + v1[3] * sigm(bf_hi(gg.w)));
;                     *(u32x4*)(E.Z + (size_t)(row0 + ai * 128 + m * 16) * NIN + 4096 + col0 + bj * 128) = w; }
;             EPI_FENCE; }
.LBB0_295:
	s_and_b64 vcc, exec, s[8:9]
	s_cbranch_vccz .LBB0_298
	v_lshrrev_b32_e32 v244, 2, v201
	v_and_b32_e32 v245, 3, v201
	v_lshl_add_u32 v243, v245, 4, v244
	v_lshlrev_b32_e32 v243, 2, v243
	v_and_b32_e32 v246, 15, v201
	v_sub_u32_e32 v244, v244, v246
	v_lshrrev_b32_e32 v246, 4, v201
	v_sub_u32_e32 v245, v245, v246
	v_lshlrev_b32_e32 v245, 4, v245
	v_mul_lo_u32 v244, v244, s69
	v_add_u32_e32 v230, v244, v245
	v_ashrrev_i32_e32 v231, 31, v230
	v_ashrrev_i32_e32 v213, 31, v212
	v_mov_b64_e32 v[214:215], s[70:71]
	s_waitcnt lgkmcnt(0)
	v_mad_i64_i32 v[130:131], s[8:9], v210, s69, v[214:215]
	v_lshlrev_b64 v[216:217], 1, v[212:213]
	v_lshl_add_u64 v[130:131], v[130:131], 0, v[216:217]
	v_add_co_u32_e32 v224, vcc, 0x2000, v130
	s_mov_b64 s[20:21], 0x2000
	s_nop 0
	v_addc_co_u32_e32 v225, vcc, 0, v131, vcc
	v_lshl_add_u64 v[132:133], v[130:131], 0, s[20:21]
	global_load_dwordx4 v[190:193], v[224:225], off
	global_load_dwordx4 v[186:189], v[132:133], off offset:-2048
	global_load_dwordx4 v[182:185], v[132:133], off offset:256
	global_load_dwordx4 v[178:181], v[132:133], off offset:-1792
	v_or_b32_e32 v0, 16, v210
	v_mad_i64_i32 v[130:131], s[8:9], v0, s69, v[214:215]
	v_lshl_add_u64 v[130:131], v[130:131], 0, v[216:217]
	v_add_co_u32_e32 v222, vcc, s3, v130
	v_or_b32_e32 v0, 32, v210
	v_lshl_add_u64 v[132:133], v[130:131], 0, s[20:21]
	v_addc_co_u32_e32 v223, vcc, 0, v131, vcc
	v_mad_i64_i32 v[130:131], s[8:9], v0, s69, v[214:215]
	v_lshl_add_u64 v[130:131], v[130:131], 0, v[216:217]
	v_add_co_u32_e32 v220, vcc, s3, v130
	v_or_b32_e32 v0, 48, v210
	global_load_dwordx4 v[174:177], v[222:223], off
	global_load_dwordx4 v[170:173], v[132:133], off offset:-2048
	global_load_dwordx4 v[166:169], v[132:133], off offset:256
	global_load_dwordx4 v[162:165], v[132:133], off offset:-1792
	v_lshl_add_u64 v[132:133], v[130:131], 0, s[20:21]
	v_addc_co_u32_e32 v221, vcc, 0, v131, vcc
	v_mad_i64_i32 v[130:131], s[8:9], v0, s69, v[214:215]
	v_lshl_add_u64 v[130:131], v[130:131], 0, v[216:217]
	v_add_co_u32_e32 v218, vcc, s3, v130
	global_load_dwordx4 v[158:161], v[220:221], off
	global_load_dwordx4 v[154:157], v[132:133], off offset:-2048
	global_load_dwordx4 v[150:153], v[132:133], off offset:256
	global_load_dwordx4 v[146:149], v[132:133], off offset:-1792
	v_lshl_add_u64 v[132:133], v[130:131], 0, s[20:21]
	v_addc_co_u32_e32 v219, vcc, 0, v131, vcc
	global_load_dwordx4 v[138:141], v[218:219], off
	global_load_dwordx4 v[142:145], v[132:133], off offset:-2048
	global_load_dwordx4 v[134:137], v[132:133], off offset:256
	s_nop 0
	global_load_dwordx4 v[130:133], v[132:133], off offset:-1792
	s_waitcnt vmcnt(0)
	v_lshlrev_b32_e32 v0, 16, v190
	v_mul_f32_e32 v0, 0xbfb8aa3b, v0
	v_exp_f32_e32 v0, v0
	v_lshlrev_b32_e32 v228, 16, v186
	v_and_b32_e32 v229, 0xffff0000, v186
	v_add_f32_e32 v0, 1.0, v0
	v_rcp_f32_e32 v226, v0
	v_and_b32_e32 v0, 0xffff0000, v190
	v_mul_f32_e32 v0, 0xbfb8aa3b, v0
	v_exp_f32_e32 v0, v0
	s_nop 0
	v_add_f32_e32 v0, 1.0, v0
	v_rcp_f32_e32 v227, v0
	v_lshlrev_b32_e32 v0, 16, v191
	v_mul_f32_e32 v0, 0xbfb8aa3b, v0
	v_exp_f32_e32 v0, v0
	v_pk_fma_f32 v[226:227], v[126:127], v[226:227], v[228:229]
	v_add_f32_e32 v0, 1.0, v0
	v_rcp_f32_e32 v190, v0
	v_and_b32_e32 v0, 0xffff0000, v191
	v_mul_f32_e32 v0, 0xbfb8aa3b, v0
	v_exp_f32_e32 v0, v0
	v_cvt_pk_bf16_f32 v186, v226, v227
	v_lshlrev_b32_e32 v226, 16, v187
	v_and_b32_e32 v227, 0xffff0000, v187
	v_add_f32_e32 v0, 1.0, v0
	v_rcp_f32_e32 v191, v0
	v_lshlrev_b32_e32 v0, 16, v192
	v_mul_f32_e32 v0, 0xbfb8aa3b, v0
	v_exp_f32_e32 v0, v0
	v_pk_fma_f32 v[190:191], v[128:129], v[190:191], v[226:227]
	v_lshlrev_b32_e32 v226, 16, v188
	v_cvt_pk_bf16_f32 v187, v190, v191
	v_add_f32_e32 v0, 1.0, v0
	v_rcp_f32_e32 v190, v0
	v_and_b32_e32 v0, 0xffff0000, v192
	v_mul_f32_e32 v0, 0xbfb8aa3b, v0
	v_exp_f32_e32 v0, v0
	v_and_b32_e32 v227, 0xffff0000, v188
	v_lshlrev_b32_e32 v192, 16, v189
	v_add_f32_e32 v0, 1.0, v0
	v_rcp_f32_e32 v191, v0
	v_lshlrev_b32_e32 v0, 16, v193
	v_mul_f32_e32 v0, 0xbfb8aa3b, v0
	v_exp_f32_e32 v0, v0
	v_pk_fma_f32 v[190:191], v[122:123], v[190:191], v[226:227]
	v_add_f32_e32 v0, 1.0, v0
	v_cvt_pk_bf16_f32 v188, v190, v191
	v_rcp_f32_e32 v190, v0
	v_and_b32_e32 v0, 0xffff0000, v193
	v_mul_f32_e32 v0, 0xbfb8aa3b, v0
	v_exp_f32_e32 v0, v0
	v_and_b32_e32 v193, 0xffff0000, v189
	v_add_f32_e32 v0, 1.0, v0
	v_rcp_f32_e32 v191, v0
	v_lshlrev_b32_e32 v0, 16, v182
	v_mul_f32_e32 v0, 0xbfb8aa3b, v0
	v_exp_f32_e32 v0, v0
	v_pk_fma_f32 v[190:191], v[124:125], v[190:191], v[192:193]
	v_add_f32_e32 v0, 1.0, v0
	v_cvt_pk_bf16_f32 v189, v190, v191
	v_lshl_add_u64 v[224:225], v[224:225], 0, v[230:231]
	ds_bpermute_b32 v244, v243, v186
	ds_bpermute_b32 v245, v243, v187
	ds_bpermute_b32 v246, v243, v188
	ds_bpermute_b32 v247, v243, v189
	s_nop 1
	v_rcp_f32_e32 v186, v0
	v_and_b32_e32 v0, 0xffff0000, v182
	v_mul_f32_e32 v0, 0xbfb8aa3b, v0
	v_exp_f32_e32 v0, v0
	v_lshlrev_b32_e32 v188, 16, v178
	v_and_b32_e32 v189, 0xffff0000, v178
	v_add_f32_e32 v0, 1.0, v0
	v_rcp_f32_e32 v187, v0
	v_lshlrev_b32_e32 v0, 16, v183
	v_mul_f32_e32 v0, 0xbfb8aa3b, v0
	v_exp_f32_e32 v0, v0
	v_pk_fma_f32 v[186:187], v[118:119], v[186:187], v[188:189]
	v_add_f32_e32 v0, 1.0, v0
	v_rcp_f32_e32 v182, v0
	v_and_b32_e32 v0, 0xffff0000, v183
	v_mul_f32_e32 v0, 0xbfb8aa3b, v0
	v_exp_f32_e32 v0, v0
	v_cvt_pk_bf16_f32 v178, v186, v187
	v_lshlrev_b32_e32 v186, 16, v179
	v_and_b32_e32 v187, 0xffff0000, v179
	v_add_f32_e32 v0, 1.0, v0
	v_rcp_f32_e32 v183, v0
	v_lshlrev_b32_e32 v0, 16, v184
	v_mul_f32_e32 v0, 0xbfb8aa3b, v0
	v_exp_f32_e32 v0, v0
	v_pk_fma_f32 v[182:183], v[120:121], v[182:183], v[186:187]
	v_lshlrev_b32_e32 v186, 16, v180
	v_cvt_pk_bf16_f32 v179, v182, v183
	v_add_f32_e32 v0, 1.0, v0
	v_rcp_f32_e32 v182, v0
	v_and_b32_e32 v0, 0xffff0000, v184
	v_mul_f32_e32 v0, 0xbfb8aa3b, v0
	v_exp_f32_e32 v0, v0
	v_and_b32_e32 v187, 0xffff0000, v180
	v_lshlrev_b32_e32 v184, 16, v181
	v_add_f32_e32 v0, 1.0, v0
	v_rcp_f32_e32 v183, v0
	v_lshlrev_b32_e32 v0, 16, v185
	v_mul_f32_e32 v0, 0xbfb8aa3b, v0
	v_exp_f32_e32 v0, v0
	v_pk_fma_f32 v[182:183], v[114:115], v[182:183], v[186:187]
	v_add_f32_e32 v0, 1.0, v0
	v_cvt_pk_bf16_f32 v180, v182, v183
	v_rcp_f32_e32 v182, v0
	v_and_b32_e32 v0, 0xffff0000, v185
	v_mul_f32_e32 v0, 0xbfb8aa3b, v0
	v_exp_f32_e32 v0, v0
	v_and_b32_e32 v185, 0xffff0000, v181
	v_add_f32_e32 v0, 1.0, v0
	v_rcp_f32_e32 v183, v0
	v_lshlrev_b32_e32 v0, 16, v174
	v_mul_f32_e32 v0, 0xbfb8aa3b, v0
	v_exp_f32_e32 v0, v0
	v_pk_fma_f32 v[182:183], v[116:117], v[182:183], v[184:185]
	v_add_f32_e32 v0, 1.0, v0
	v_cvt_pk_bf16_f32 v181, v182, v183
	s_waitcnt lgkmcnt(0)
; __device__ __forceinline__ unsigned cvt_pk_bf16(float lo, float hi) { f32x2 v = {lo, hi}; bf16x2_t b = __builtin_convertvector(v, bf16x2_t); return __builtin_bit_cast(unsigned, b); }
; __device__ __forceinline__ float bf_lo(unsigned w) { return __uint_as_float(w << 16); }
; __device__ __forceinline__ float bf_hi(unsigned w) { return __uint_as_float(w & 0xffff0000u); }
; __device__ __forceinline__ float sigm(float v) { return __builtin_amdgcn_rcpf(1.0f + __builtin_amdgcn_exp2f(-1.44269504089f * v)); }
; __device__ __forceinline__ void epi_run(const Epi& E, f32x4 (&acc)[2][2][4][2], const Unit& u, int wr, int wc, int fr, int fq) {
;     ...
;                 for (int bj = 0; bj < 2; ++bj) { const bf16_t* gp = E.Z + (size_t)(row0 + ai * 128 + m * 16) * NIN + 4096 + col0 + bj * 128; g[m][bj] = *(const u32x4*)gp; c[m][bj] = *(const u32x4*)(gp - 1024); }
; #pragma unroll
;             for (int m = 0; m < 4; ++m)
; #pragma unroll
;                 for (int bj = 0; bj < 2; ++bj) { const f32x4 v0 = acc[ai][bj][m][0], v1 = acc[ai][bj][m][1]; const u32x4 gg = g[m][bj], cc = c[m][bj]; u32x4 w;
;                     w.x = cvt_pk_bf16(bf_lo(cc.x) + v0[0] * sigm(bf_lo(gg.x)), bf_hi(cc.x) + v0[1] * sigm(bf_hi(gg.x))); w.y = cvt_pk_bf16(bf_lo(cc.y) + v0[2] * sigm(bf_lo(gg.y)), bf_hi(cc.y) + v0[3] * sigm(bf_hi(gg.y)));
;                     w.z = cvt_pk_bf16(bf_lo(cc.z) + v1[0] * sigm(bf_lo(gg.z)), bf_hi(cc.z) + v1[1] * sigm(bf_hi(gg.z))); w.w = cvt_pk_bf16(bf_lo(cc.w) + v1[2] * sigm(bf_lo(gg.w)), bf_hi(cc.w) + v1[3] * sigm(bf_hi(gg.w)));
;                     *(u32x4*)(E.Z + (size_t)(row0 + ai * 128 + m * 16) * NIN + 4096 + col0 + bj * 128) = w; }
	global_store_dwordx4 v[224:225], v[244:247], off
	s_nop 1
	ds_bpermute_b32 v244, v243, v178
	ds_bpermute_b32 v245, v243, v179
	ds_bpermute_b32 v246, v243, v180
	ds_bpermute_b32 v247, v243, v181
	s_nop 1
	v_rcp_f32_e32 v178, v0
	v_and_b32_e32 v0, 0xffff0000, v174
	v_mul_f32_e32 v0, 0xbfb8aa3b, v0
	v_exp_f32_e32 v0, v0
	v_lshlrev_b32_e32 v180, 16, v170
	v_and_b32_e32 v181, 0xffff0000, v170
	v_add_f32_e32 v0, 1.0, v0
	v_rcp_f32_e32 v179, v0
	v_lshlrev_b32_e32 v0, 16, v175
	v_mul_f32_e32 v0, 0xbfb8aa3b, v0
	v_exp_f32_e32 v0, v0
	v_pk_fma_f32 v[178:179], v[110:111], v[178:179], v[180:181]
	v_add_f32_e32 v0, 1.0, v0
	v_rcp_f32_e32 v174, v0
	v_and_b32_e32 v0, 0xffff0000, v175
	v_mul_f32_e32 v0, 0xbfb8aa3b, v0
	v_exp_f32_e32 v0, v0
	v_cvt_pk_bf16_f32 v170, v178, v179
	v_lshlrev_b32_e32 v178, 16, v171
	v_and_b32_e32 v179, 0xffff0000, v171
	v_add_f32_e32 v0, 1.0, v0
	v_rcp_f32_e32 v175, v0
	v_lshlrev_b32_e32 v0, 16, v176
	v_mul_f32_e32 v0, 0xbfb8aa3b, v0
	v_exp_f32_e32 v0, v0
	v_pk_fma_f32 v[174:175], v[112:113], v[174:175], v[178:179]
	v_lshlrev_b32_e32 v178, 16, v172
	v_cvt_pk_bf16_f32 v171, v174, v175
	v_add_f32_e32 v0, 1.0, v0
	v_rcp_f32_e32 v174, v0
	v_and_b32_e32 v0, 0xffff0000, v176
	v_mul_f32_e32 v0, 0xbfb8aa3b, v0
	v_exp_f32_e32 v0, v0
	v_and_b32_e32 v179, 0xffff0000, v172
	v_lshlrev_b32_e32 v176, 16, v173
	v_add_f32_e32 v0, 1.0, v0
	v_rcp_f32_e32 v175, v0
	v_lshlrev_b32_e32 v0, 16, v177
	v_mul_f32_e32 v0, 0xbfb8aa3b, v0
	v_exp_f32_e32 v0, v0
	v_pk_fma_f32 v[174:175], v[106:107], v[174:175], v[178:179]
	v_add_f32_e32 v0, 1.0, v0
	v_cvt_pk_bf16_f32 v172, v174, v175
	v_rcp_f32_e32 v174, v0
	v_and_b32_e32 v0, 0xffff0000, v177
	v_mul_f32_e32 v0, 0xbfb8aa3b, v0
	v_exp_f32_e32 v0, v0
	v_and_b32_e32 v177, 0xffff0000, v173
	v_add_f32_e32 v0, 1.0, v0
	v_rcp_f32_e32 v175, v0
	v_lshlrev_b32_e32 v0, 16, v166
	v_mul_f32_e32 v0, 0xbfb8aa3b, v0
	v_exp_f32_e32 v0, v0
	v_pk_fma_f32 v[174:175], v[108:109], v[174:175], v[176:177]
	v_add_f32_e32 v0, 1.0, v0
	v_cvt_pk_bf16_f32 v173, v174, v175
	s_waitcnt lgkmcnt(0)
	global_store_dwordx4 v[224:225], v[244:247], off offset:256
	v_lshl_add_u64 v[222:223], v[222:223], 0, v[230:231]
	ds_bpermute_b32 v244, v243, v170
	ds_bpermute_b32 v245, v243, v171
	ds_bpermute_b32 v246, v243, v172
	ds_bpermute_b32 v247, v243, v173
	s_nop 1
	v_rcp_f32_e32 v170, v0
	v_and_b32_e32 v0, 0xffff0000, v166
	v_mul_f32_e32 v0, 0xbfb8aa3b, v0
	v_exp_f32_e32 v0, v0
	v_lshlrev_b32_e32 v172, 16, v162
	v_and_b32_e32 v173, 0xffff0000, v162
	v_add_f32_e32 v0, 1.0, v0
	v_rcp_f32_e32 v171, v0
	v_lshlrev_b32_e32 v0, 16, v167
	v_mul_f32_e32 v0, 0xbfb8aa3b, v0
	v_exp_f32_e32 v0, v0
	v_pk_fma_f32 v[170:171], v[102:103], v[170:171], v[172:173]
	v_add_f32_e32 v0, 1.0, v0
	v_rcp_f32_e32 v166, v0
	v_and_b32_e32 v0, 0xffff0000, v167
	v_mul_f32_e32 v0, 0xbfb8aa3b, v0
	v_exp_f32_e32 v0, v0
	v_cvt_pk_bf16_f32 v162, v170, v171
	v_lshlrev_b32_e32 v170, 16, v163
	v_and_b32_e32 v171, 0xffff0000, v163
	v_add_f32_e32 v0, 1.0, v0
	v_rcp_f32_e32 v167, v0
	v_lshlrev_b32_e32 v0, 16, v168
	v_mul_f32_e32 v0, 0xbfb8aa3b, v0
	v_exp_f32_e32 v0, v0
	v_pk_fma_f32 v[166:167], v[104:105], v[166:167], v[170:171]
	v_lshlrev_b32_e32 v170, 16, v164
	v_cvt_pk_bf16_f32 v163, v166, v167
	v_add_f32_e32 v0, 1.0, v0
	v_rcp_f32_e32 v166, v0
	v_and_b32_e32 v0, 0xffff0000, v168
	v_mul_f32_e32 v0, 0xbfb8aa3b, v0
	v_exp_f32_e32 v0, v0
	v_and_b32_e32 v171, 0xffff0000, v164
	v_lshlrev_b32_e32 v168, 16, v165
	v_add_f32_e32 v0, 1.0, v0
	v_rcp_f32_e32 v167, v0
	v_lshlrev_b32_e32 v0, 16, v169
	v_mul_f32_e32 v0, 0xbfb8aa3b, v0
	v_exp_f32_e32 v0, v0
	v_pk_fma_f32 v[166:167], v[94:95], v[166:167], v[170:171]
	v_add_f32_e32 v0, 1.0, v0
	v_cvt_pk_bf16_f32 v164, v166, v167
	v_rcp_f32_e32 v166, v0
	v_and_b32_e32 v0, 0xffff0000, v169
	v_mul_f32_e32 v0, 0xbfb8aa3b, v0
	v_exp_f32_e32 v0, v0
	v_and_b32_e32 v169, 0xffff0000, v165
	v_add_f32_e32 v0, 1.0, v0
	v_rcp_f32_e32 v167, v0
	v_lshlrev_b32_e32 v0, 16, v158
	v_mul_f32_e32 v0, 0xbfb8aa3b, v0
	v_exp_f32_e32 v0, v0
	v_pk_fma_f32 v[166:167], v[96:97], v[166:167], v[168:169]
	v_add_f32_e32 v0, 1.0, v0
	v_cvt_pk_bf16_f32 v165, v166, v167
	s_waitcnt lgkmcnt(0)
	global_store_dwordx4 v[222:223], v[244:247], off
	s_nop 1
	ds_bpermute_b32 v244, v243, v162
	ds_bpermute_b32 v245, v243, v163
	ds_bpermute_b32 v246, v243, v164
	ds_bpermute_b32 v247, v243, v165
	s_nop 1
	v_rcp_f32_e32 v162, v0
	v_and_b32_e32 v0, 0xffff0000, v158
	v_mul_f32_e32 v0, 0xbfb8aa3b, v0
	v_exp_f32_e32 v0, v0
	v_lshlrev_b32_e32 v164, 16, v154
	v_and_b32_e32 v165, 0xffff0000, v154
	v_add_f32_e32 v0, 1.0, v0
	v_rcp_f32_e32 v163, v0
	v_lshlrev_b32_e32 v0, 16, v159
	v_mul_f32_e32 v0, 0xbfb8aa3b, v0
	v_exp_f32_e32 v0, v0
	v_pk_fma_f32 v[162:163], v[98:99], v[162:163], v[164:165]
	v_add_f32_e32 v0, 1.0, v0
	v_rcp_f32_e32 v158, v0
	v_and_b32_e32 v0, 0xffff0000, v159
	v_mul_f32_e32 v0, 0xbfb8aa3b, v0
	v_exp_f32_e32 v0, v0
	v_cvt_pk_bf16_f32 v154, v162, v163
	v_lshlrev_b32_e32 v162, 16, v155
	v_and_b32_e32 v163, 0xffff0000, v155
	v_add_f32_e32 v0, 1.0, v0
	v_rcp_f32_e32 v159, v0
	v_lshlrev_b32_e32 v0, 16, v160
	v_mul_f32_e32 v0, 0xbfb8aa3b, v0
	v_exp_f32_e32 v0, v0
	v_pk_fma_f32 v[158:159], v[100:101], v[158:159], v[162:163]
	v_lshlrev_b32_e32 v162, 16, v156
	v_cvt_pk_bf16_f32 v155, v158, v159
	v_add_f32_e32 v0, 1.0, v0
	v_rcp_f32_e32 v158, v0
	v_and_b32_e32 v0, 0xffff0000, v160
	v_mul_f32_e32 v0, 0xbfb8aa3b, v0
	v_exp_f32_e32 v0, v0
	v_and_b32_e32 v163, 0xffff0000, v156
	v_lshlrev_b32_e32 v160, 16, v157
	v_add_f32_e32 v0, 1.0, v0
	v_rcp_f32_e32 v159, v0
	v_lshlrev_b32_e32 v0, 16, v161
	v_mul_f32_e32 v0, 0xbfb8aa3b, v0
	v_exp_f32_e32 v0, v0
	v_pk_fma_f32 v[158:159], v[90:91], v[158:159], v[162:163]
	v_add_f32_e32 v0, 1.0, v0
	v_cvt_pk_bf16_f32 v156, v158, v159
	v_rcp_f32_e32 v158, v0
	v_and_b32_e32 v0, 0xffff0000, v161
	v_mul_f32_e32 v0, 0xbfb8aa3b, v0
	v_exp_f32_e32 v0, v0
	v_and_b32_e32 v161, 0xffff0000, v157
	v_add_f32_e32 v0, 1.0, v0
	v_rcp_f32_e32 v159, v0
	v_lshlrev_b32_e32 v0, 16, v150
	v_mul_f32_e32 v0, 0xbfb8aa3b, v0
	v_exp_f32_e32 v0, v0
	v_pk_fma_f32 v[158:159], v[92:93], v[158:159], v[160:161]
	v_add_f32_e32 v0, 1.0, v0
	v_cvt_pk_bf16_f32 v157, v158, v159
	s_waitcnt lgkmcnt(0)
; __device__ __forceinline__ unsigned cvt_pk_bf16(float lo, float hi) { f32x2 v = {lo, hi}; bf16x2_t b = __builtin_convertvector(v, bf16x2_t); return __builtin_bit_cast(unsigned, b); }
; __device__ __forceinline__ float bf_lo(unsigned w) { return __uint_as_float(w << 16); }
; __device__ __forceinline__ float bf_hi(unsigned w) { return __uint_as_float(w & 0xffff0000u); }
; __device__ __forceinline__ float sigm(float v) { return __builtin_amdgcn_rcpf(1.0f + __builtin_amdgcn_exp2f(-1.44269504089f * v)); }
; __device__ __forceinline__ void epi_run(const Epi& E, f32x4 (&acc)[2][2][4][2], const Unit& u, int wr, int wc, int fr, int fq) {
;     ...
;                 for (int bj = 0; bj < 2; ++bj) { const bf16_t* gp = E.Z + (size_t)(row0 + ai * 128 + m * 16) * NIN + 4096 + col0 + bj * 128; g[m][bj] = *(const u32x4*)gp; c[m][bj] = *(const u32x4*)(gp - 1024); }
; #pragma unroll
;             for (int m = 0; m < 4; ++m)
; #pragma unroll
;                 for (int bj = 0; bj < 2; ++bj) { const f32x4 v0 = acc[ai][bj][m][0], v1 = acc[ai][bj][m][1]; const u32x4 gg = g[m][bj], cc = c[m][bj]; u32x4 w;
;                     w.x = cvt_pk_bf16(bf_lo(cc.x) + v0[0] * sigm(bf_lo(gg.x)), bf_hi(cc.x) + v0[1] * sigm(bf_hi(gg.x))); w.y = cvt_pk_bf16(bf_lo(cc.y) + v0[2] * sigm(bf_lo(gg.y)), bf_hi(cc.y) + v0[3] * sigm(bf_hi(gg.y)));
;                     w.z = cvt_pk_bf16(bf_lo(cc.z) + v1[0] * sigm(bf_lo(gg.z)), bf_hi(cc.z) + v1[1] * sigm(bf_hi(gg.z))); w.w = cvt_pk_bf16(bf_lo(cc.w) + v1[2] * sigm(bf_lo(gg.w)), bf_hi(cc.w) + v1[3] * sigm(bf_hi(gg.w)));
;                     *(u32x4*)(E.Z + (size_t)(row0 + ai * 128 + m * 16) * NIN + 4096 + col0 + bj * 128) = w; }
	global_store_dwordx4 v[222:223], v[244:247], off offset:256
	v_lshl_add_u64 v[220:221], v[220:221], 0, v[230:231]
	ds_bpermute_b32 v244, v243, v154
	ds_bpermute_b32 v245, v243, v155
	ds_bpermute_b32 v246, v243, v156
	ds_bpermute_b32 v247, v243, v157
	s_nop 1
	v_rcp_f32_e32 v154, v0
	v_and_b32_e32 v0, 0xffff0000, v150
	v_mul_f32_e32 v0, 0xbfb8aa3b, v0
	v_exp_f32_e32 v0, v0
	v_lshlrev_b32_e32 v156, 16, v146
	v_and_b32_e32 v157, 0xffff0000, v146
	v_add_f32_e32 v0, 1.0, v0
	v_rcp_f32_e32 v155, v0
	v_lshlrev_b32_e32 v0, 16, v151
	v_mul_f32_e32 v0, 0xbfb8aa3b, v0
	v_exp_f32_e32 v0, v0
	v_pk_fma_f32 v[154:155], v[86:87], v[154:155], v[156:157]
	v_add_f32_e32 v0, 1.0, v0
	v_rcp_f32_e32 v150, v0
	v_and_b32_e32 v0, 0xffff0000, v151
	v_mul_f32_e32 v0, 0xbfb8aa3b, v0
	v_exp_f32_e32 v0, v0
	v_cvt_pk_bf16_f32 v146, v154, v155
	v_lshlrev_b32_e32 v154, 16, v147
	v_and_b32_e32 v155, 0xffff0000, v147
	v_add_f32_e32 v0, 1.0, v0
	v_rcp_f32_e32 v151, v0
	v_lshlrev_b32_e32 v0, 16, v152
	v_mul_f32_e32 v0, 0xbfb8aa3b, v0
	v_exp_f32_e32 v0, v0
	v_pk_fma_f32 v[150:151], v[88:89], v[150:151], v[154:155]
	v_lshlrev_b32_e32 v154, 16, v148
	v_cvt_pk_bf16_f32 v147, v150, v151
	v_add_f32_e32 v0, 1.0, v0
	v_rcp_f32_e32 v150, v0
	v_and_b32_e32 v0, 0xffff0000, v152
	v_mul_f32_e32 v0, 0xbfb8aa3b, v0
	v_exp_f32_e32 v0, v0
	v_and_b32_e32 v155, 0xffff0000, v148
	v_lshlrev_b32_e32 v152, 16, v149
	v_add_f32_e32 v0, 1.0, v0
	v_rcp_f32_e32 v151, v0
	v_lshlrev_b32_e32 v0, 16, v153
	v_mul_f32_e32 v0, 0xbfb8aa3b, v0
	v_exp_f32_e32 v0, v0
	v_pk_fma_f32 v[150:151], v[78:79], v[150:151], v[154:155]
	v_add_f32_e32 v0, 1.0, v0
	v_cvt_pk_bf16_f32 v148, v150, v151
	v_rcp_f32_e32 v150, v0
	v_and_b32_e32 v0, 0xffff0000, v153
	v_mul_f32_e32 v0, 0xbfb8aa3b, v0
	v_exp_f32_e32 v0, v0
	v_and_b32_e32 v153, 0xffff0000, v149
	v_add_f32_e32 v0, 1.0, v0
	v_rcp_f32_e32 v151, v0
	v_lshlrev_b32_e32 v0, 16, v138
	v_mul_f32_e32 v0, 0xbfb8aa3b, v0
	v_exp_f32_e32 v0, v0
	v_pk_fma_f32 v[150:151], v[80:81], v[150:151], v[152:153]
	v_add_f32_e32 v0, 1.0, v0
	v_cvt_pk_bf16_f32 v149, v150, v151
	s_waitcnt lgkmcnt(0)
	global_store_dwordx4 v[220:221], v[244:247], off
	s_nop 1
	ds_bpermute_b32 v244, v243, v146
	ds_bpermute_b32 v245, v243, v147
	ds_bpermute_b32 v246, v243, v148
	ds_bpermute_b32 v247, v243, v149
	s_nop 1
	v_rcp_f32_e32 v146, v0
	v_and_b32_e32 v0, 0xffff0000, v138
	v_mul_f32_e32 v0, 0xbfb8aa3b, v0
	v_exp_f32_e32 v0, v0
	v_lshlrev_b32_e32 v148, 16, v142
	v_and_b32_e32 v149, 0xffff0000, v142
	v_lshlrev_b32_e32 v142, 16, v143
	v_add_f32_e32 v0, 1.0, v0
	v_rcp_f32_e32 v147, v0
	v_lshlrev_b32_e32 v0, 16, v139
	v_mul_f32_e32 v0, 0xbfb8aa3b, v0
	v_exp_f32_e32 v0, v0
	v_pk_fma_f32 v[146:147], v[82:83], v[146:147], v[148:149]
	v_and_b32_e32 v143, 0xffff0000, v143
	v_cvt_pk_bf16_f32 v138, v146, v147
	v_add_f32_e32 v0, 1.0, v0
	v_rcp_f32_e32 v146, v0
	v_and_b32_e32 v0, 0xffff0000, v139
	v_mul_f32_e32 v0, 0xbfb8aa3b, v0
	v_exp_f32_e32 v0, v0
	s_nop 0
	v_add_f32_e32 v0, 1.0, v0
	v_rcp_f32_e32 v147, v0
	v_lshlrev_b32_e32 v0, 16, v140
	v_mul_f32_e32 v0, 0xbfb8aa3b, v0
	v_exp_f32_e32 v0, v0
	v_pk_fma_f32 v[142:143], v[84:85], v[146:147], v[142:143]
	v_lshlrev_b32_e32 v146, 16, v144
	v_cvt_pk_bf16_f32 v139, v142, v143
	v_add_f32_e32 v0, 1.0, v0
	v_rcp_f32_e32 v142, v0
	v_and_b32_e32 v0, 0xffff0000, v140
	v_mul_f32_e32 v0, 0xbfb8aa3b, v0
	v_exp_f32_e32 v0, v0
	v_and_b32_e32 v147, 0xffff0000, v144
	v_lshlrev_b32_e32 v144, 16, v145
	v_and_b32_e32 v145, 0xffff0000, v145
	v_add_f32_e32 v0, 1.0, v0
	v_rcp_f32_e32 v143, v0
	v_lshlrev_b32_e32 v0, 16, v141
	v_mul_f32_e32 v0, 0xbfb8aa3b, v0
	v_exp_f32_e32 v0, v0
	v_pk_fma_f32 v[142:143], v[74:75], v[142:143], v[146:147]
	v_add_f32_e32 v0, 1.0, v0
	v_cvt_pk_bf16_f32 v140, v142, v143
	v_rcp_f32_e32 v142, v0
	v_and_b32_e32 v0, 0xffff0000, v141
	v_mul_f32_e32 v0, 0xbfb8aa3b, v0
	v_exp_f32_e32 v0, v0
	s_nop 0
	v_add_f32_e32 v0, 1.0, v0
	v_rcp_f32_e32 v143, v0
	v_lshlrev_b32_e32 v0, 16, v134
	v_mul_f32_e32 v0, 0xbfb8aa3b, v0
	v_exp_f32_e32 v0, v0
	v_pk_fma_f32 v[142:143], v[76:77], v[142:143], v[144:145]
	v_add_f32_e32 v0, 1.0, v0
	v_cvt_pk_bf16_f32 v141, v142, v143
	s_waitcnt lgkmcnt(0)
	global_store_dwordx4 v[220:221], v[244:247], off offset:256
	v_lshl_add_u64 v[218:219], v[218:219], 0, v[230:231]
	ds_bpermute_b32 v244, v243, v138
	ds_bpermute_b32 v245, v243, v139
	ds_bpermute_b32 v246, v243, v140
	ds_bpermute_b32 v247, v243, v141
	s_nop 1
	v_rcp_f32_e32 v138, v0
	v_and_b32_e32 v0, 0xffff0000, v134
	v_mul_f32_e32 v0, 0xbfb8aa3b, v0
	v_exp_f32_e32 v0, v0
	v_lshlrev_b32_e32 v140, 16, v130
	v_and_b32_e32 v141, 0xffff0000, v130
	v_add_f32_e32 v0, 1.0, v0
	v_rcp_f32_e32 v139, v0
	v_lshlrev_b32_e32 v0, 16, v135
	v_mul_f32_e32 v0, 0xbfb8aa3b, v0
	v_exp_f32_e32 v0, v0
	v_pk_fma_f32 v[138:139], v[70:71], v[138:139], v[140:141]
	v_add_f32_e32 v0, 1.0, v0
	v_rcp_f32_e32 v134, v0
	v_and_b32_e32 v0, 0xffff0000, v135
	v_mul_f32_e32 v0, 0xbfb8aa3b, v0
	v_exp_f32_e32 v0, v0
	v_cvt_pk_bf16_f32 v130, v138, v139
	v_lshlrev_b32_e32 v138, 16, v131
	v_and_b32_e32 v139, 0xffff0000, v131
	v_add_f32_e32 v0, 1.0, v0
	v_rcp_f32_e32 v135, v0
	v_lshlrev_b32_e32 v0, 16, v136
	v_mul_f32_e32 v0, 0xbfb8aa3b, v0
	v_exp_f32_e32 v0, v0
	v_pk_fma_f32 v[134:135], v[72:73], v[134:135], v[138:139]
	v_lshlrev_b32_e32 v138, 16, v132
	v_cvt_pk_bf16_f32 v131, v134, v135
	v_add_f32_e32 v0, 1.0, v0
	v_rcp_f32_e32 v134, v0
	v_and_b32_e32 v0, 0xffff0000, v136
	v_mul_f32_e32 v0, 0xbfb8aa3b, v0
	v_exp_f32_e32 v0, v0
	v_and_b32_e32 v139, 0xffff0000, v132
	v_lshlrev_b32_e32 v136, 16, v133
	v_add_f32_e32 v0, 1.0, v0
	v_rcp_f32_e32 v135, v0
	v_lshlrev_b32_e32 v0, 16, v137
	v_mul_f32_e32 v0, 0xbfb8aa3b, v0
	v_exp_f32_e32 v0, v0
	v_pk_fma_f32 v[134:135], v[66:67], v[134:135], v[138:139]
	v_add_f32_e32 v0, 1.0, v0
	v_cvt_pk_bf16_f32 v132, v134, v135
	v_rcp_f32_e32 v134, v0
	v_and_b32_e32 v0, 0xffff0000, v137
	v_mul_f32_e32 v0, 0xbfb8aa3b, v0
	v_exp_f32_e32 v0, v0
	v_and_b32_e32 v137, 0xffff0000, v133
	v_add_f32_e32 v0, 1.0, v0
	v_rcp_f32_e32 v135, v0
	v_add_u32_e32 v0, 0x80, v210
	v_pk_fma_f32 v[134:135], v[68:69], v[134:135], v[136:137]
	s_nop 0
	v_cvt_pk_bf16_f32 v133, v134, v135
	s_waitcnt lgkmcnt(0)
; __device__ __forceinline__ unsigned cvt_pk_bf16(float lo, float hi) { f32x2 v = {lo, hi}; bf16x2_t b = __builtin_convertvector(v, bf16x2_t); return __builtin_bit_cast(unsigned, b); }
; __device__ __forceinline__ float bf_lo(unsigned w) { return __uint_as_float(w << 16); }
; __device__ __forceinline__ float bf_hi(unsigned w) { return __uint_as_float(w & 0xffff0000u); }
; __device__ __forceinline__ float sigm(float v) { return __builtin_amdgcn_rcpf(1.0f + __builtin_amdgcn_exp2f(-1.44269504089f * v)); }
; __device__ __forceinline__ void epi_run(const Epi& E, f32x4 (&acc)[2][2][4][2], const Unit& u, int wr, int wc, int fr, int fq) {
;     ...
;         for (int ai = 0; ai < 2; ++ai) { u32x4 g[4][2], c[4][2];
; #pragma unroll
;             for (int m = 0; m < 4; ++m)
; #pragma unroll
;                 for (int bj = 0; bj < 2; ++bj) { const bf16_t* gp = E.Z + (size_t)(row0 + ai * 128 + m * 16) * NIN + 4096 + col0 + bj * 128; g[m][bj] = *(const u32x4*)gp; c[m][bj] = *(const u32x4*)(gp - 1024); }
; #pragma unroll
;             for (int m = 0; m < 4; ++m)
; #pragma unroll
;                 for (int bj = 0; bj < 2; ++bj) { const f32x4 v0 = acc[ai][bj][m][0], v1 = acc[ai][bj][m][1]; const u32x4 gg = g[m][bj], cc = c[m][bj]; u32x4 w;
;                     w.x = cvt_pk_bf16(bf_lo(cc.x) + v0[0] * sigm(bf_lo(gg.x)), bf_hi(cc.x) + v0[1] * sigm(bf_hi(gg.x))); w.y = cvt_pk_bf16(bf_lo(cc.y) + v0[2] * sigm(bf_lo(gg.y)), bf_hi(cc.y) + v0[3] * sigm(bf_hi(gg.y)));
;                     w.z = cvt_pk_bf16(bf_lo(cc.z) + v1[0] * sigm(bf_lo(gg.z)), bf_hi(cc.z) + v1[1] * sigm(bf_hi(gg.z))); w.w = cvt_pk_bf16(bf_lo(cc.w) + v1[2] * sigm(bf_lo(gg.w)), bf_hi(cc.w) + v1[3] * sigm(bf_hi(gg.w)));
;                     *(u32x4*)(E.Z + (size_t)(row0 + ai * 128 + m * 16) * NIN + 4096 + col0 + bj * 128) = w; }
	global_store_dwordx4 v[218:219], v[244:247], off
	s_nop 1
	ds_bpermute_b32 v244, v243, v130
	ds_bpermute_b32 v245, v243, v131
	ds_bpermute_b32 v246, v243, v132
	ds_bpermute_b32 v247, v243, v133
	s_nop 1
	v_mad_i64_i32 v[130:131], s[8:9], v0, s69, v[214:215]
	v_lshl_add_u64 v[130:131], v[130:131], 0, v[216:217]
	v_add_co_u32_e32 v192, vcc, s3, v130
	v_lshl_add_u64 v[132:133], v[130:131], 0, s[20:21]
	s_nop 0
	v_addc_co_u32_e32 v193, vcc, 0, v131, vcc
	s_waitcnt lgkmcnt(0)
	global_store_dwordx4 v[218:219], v[244:247], off offset:256
	global_load_dwordx4 v[218:221], v[192:193], off
	global_load_dwordx4 v[222:225], v[132:133], off offset:-2048
	global_load_dwordx4 v[182:185], v[132:133], off offset:256
	global_load_dwordx4 v[178:181], v[132:133], off offset:-1792
	v_add_u32_e32 v0, 0x90, v210
	v_mad_i64_i32 v[130:131], s[8:9], v0, s69, v[214:215]
	v_lshl_add_u64 v[130:131], v[130:131], 0, v[216:217]
	v_add_co_u32_e32 v190, vcc, s3, v130
	v_add_u32_e32 v0, 0xa0, v210
	v_lshl_add_u64 v[132:133], v[130:131], 0, s[20:21]
	v_addc_co_u32_e32 v191, vcc, 0, v131, vcc
	v_mad_i64_i32 v[130:131], s[8:9], v0, s69, v[214:215]
	v_lshl_add_u64 v[130:131], v[130:131], 0, v[216:217]
	v_add_co_u32_e32 v188, vcc, s3, v130
	v_add_u32_e32 v0, 0xb0, v210
	global_load_dwordx4 v[174:177], v[190:191], off
	global_load_dwordx4 v[170:173], v[132:133], off offset:-2048
	global_load_dwordx4 v[166:169], v[132:133], off offset:256
	global_load_dwordx4 v[162:165], v[132:133], off offset:-1792
	v_lshl_add_u64 v[132:133], v[130:131], 0, s[20:21]
	v_addc_co_u32_e32 v189, vcc, 0, v131, vcc
	v_mad_i64_i32 v[130:131], s[8:9], v0, s69, v[214:215]
	v_lshl_add_u64 v[130:131], v[130:131], 0, v[216:217]
	v_add_co_u32_e32 v186, vcc, s3, v130
	global_load_dwordx4 v[158:161], v[188:189], off
	global_load_dwordx4 v[154:157], v[132:133], off offset:-2048
	global_load_dwordx4 v[150:153], v[132:133], off offset:256
	global_load_dwordx4 v[146:149], v[132:133], off offset:-1792
	v_lshl_add_u64 v[132:133], v[130:131], 0, s[20:21]
	v_addc_co_u32_e32 v187, vcc, 0, v131, vcc
	global_load_dwordx4 v[142:145], v[186:187], off
	global_load_dwordx4 v[138:141], v[132:133], off offset:-2048
	global_load_dwordx4 v[134:137], v[132:133], off offset:256
	s_nop 0
	global_load_dwordx4 v[130:133], v[132:133], off offset:-1792
	s_mov_b64 s[8:9], 0
	s_waitcnt vmcnt(15)
	v_lshlrev_b32_e32 v0, 16, v218
	v_mul_f32_e32 v0, 0xbfb8aa3b, v0
	v_exp_f32_e32 v0, v0
	s_waitcnt vmcnt(14)
	v_lshlrev_b32_e32 v216, 16, v222
	v_and_b32_e32 v217, 0xffff0000, v222
	v_add_f32_e32 v0, 1.0, v0
	v_rcp_f32_e32 v214, v0
	v_and_b32_e32 v0, 0xffff0000, v218
	v_mul_f32_e32 v0, 0xbfb8aa3b, v0
	v_exp_f32_e32 v0, v0
	v_lshlrev_b32_e32 v218, 16, v223
	v_add_f32_e32 v0, 1.0, v0
	v_rcp_f32_e32 v215, v0
	v_lshlrev_b32_e32 v0, 16, v219
	v_mul_f32_e32 v0, 0xbfb8aa3b, v0
	v_exp_f32_e32 v0, v0
	v_pk_fma_f32 v[214:215], v[62:63], v[214:215], v[216:217]
	v_add_f32_e32 v0, 1.0, v0
	v_rcp_f32_e32 v216, v0
	v_and_b32_e32 v0, 0xffff0000, v219
	v_mul_f32_e32 v0, 0xbfb8aa3b, v0
	v_exp_f32_e32 v0, v0
	v_and_b32_e32 v219, 0xffff0000, v223
	v_cvt_pk_bf16_f32 v214, v214, v215
	v_add_f32_e32 v0, 1.0, v0
	v_rcp_f32_e32 v217, v0
	v_lshlrev_b32_e32 v0, 16, v220
	v_mul_f32_e32 v0, 0xbfb8aa3b, v0
	v_exp_f32_e32 v0, v0
	v_pk_fma_f32 v[216:217], v[64:65], v[216:217], v[218:219]
	v_lshlrev_b32_e32 v218, 16, v224
	v_cvt_pk_bf16_f32 v215, v216, v217
	v_add_f32_e32 v0, 1.0, v0
	v_rcp_f32_e32 v216, v0
	v_and_b32_e32 v0, 0xffff0000, v220
	v_mul_f32_e32 v0, 0xbfb8aa3b, v0
	v_exp_f32_e32 v0, v0
	v_and_b32_e32 v219, 0xffff0000, v224
	v_lshlrev_b32_e32 v220, 16, v225
	v_add_f32_e32 v0, 1.0, v0
	v_rcp_f32_e32 v217, v0
	v_lshlrev_b32_e32 v0, 16, v221
	v_mul_f32_e32 v0, 0xbfb8aa3b, v0
	v_exp_f32_e32 v0, v0
	v_pk_fma_f32 v[216:217], v[58:59], v[216:217], v[218:219]
	v_add_f32_e32 v0, 1.0, v0
	v_rcp_f32_e32 v218, v0
	v_and_b32_e32 v0, 0xffff0000, v221
	v_mul_f32_e32 v0, 0xbfb8aa3b, v0
	v_exp_f32_e32 v0, v0
	v_and_b32_e32 v221, 0xffff0000, v225
	v_cvt_pk_bf16_f32 v216, v216, v217
	v_add_f32_e32 v0, 1.0, v0
	v_rcp_f32_e32 v219, v0
	s_waitcnt vmcnt(13)
	v_lshlrev_b32_e32 v0, 16, v182
	v_mul_f32_e32 v0, 0xbfb8aa3b, v0
	v_exp_f32_e32 v0, v0
	v_pk_fma_f32 v[218:219], v[60:61], v[218:219], v[220:221]
	v_add_f32_e32 v0, 1.0, v0
	v_cvt_pk_bf16_f32 v217, v218, v219
	v_lshl_add_u64 v[192:193], v[192:193], 0, v[230:231]
	ds_bpermute_b32 v244, v243, v214
	ds_bpermute_b32 v245, v243, v215
	ds_bpermute_b32 v246, v243, v216
	ds_bpermute_b32 v247, v243, v217
	s_nop 1
	v_rcp_f32_e32 v214, v0
	v_and_b32_e32 v0, 0xffff0000, v182
	v_mul_f32_e32 v0, 0xbfb8aa3b, v0
	v_exp_f32_e32 v0, v0
	s_waitcnt vmcnt(12)
	v_lshlrev_b32_e32 v216, 16, v178
	v_and_b32_e32 v217, 0xffff0000, v178
	v_add_f32_e32 v0, 1.0, v0
	v_rcp_f32_e32 v215, v0
	v_lshlrev_b32_e32 v0, 16, v183
	v_mul_f32_e32 v0, 0xbfb8aa3b, v0
	v_exp_f32_e32 v0, v0
	v_pk_fma_f32 v[214:215], v[54:55], v[214:215], v[216:217]
	v_add_f32_e32 v0, 1.0, v0
	v_rcp_f32_e32 v182, v0
	v_and_b32_e32 v0, 0xffff0000, v183
	v_mul_f32_e32 v0, 0xbfb8aa3b, v0
	v_exp_f32_e32 v0, v0
	v_cvt_pk_bf16_f32 v178, v214, v215
	v_lshlrev_b32_e32 v214, 16, v179
	v_and_b32_e32 v215, 0xffff0000, v179
	v_add_f32_e32 v0, 1.0, v0
	v_rcp_f32_e32 v183, v0
	v_lshlrev_b32_e32 v0, 16, v184
	v_mul_f32_e32 v0, 0xbfb8aa3b, v0
	v_exp_f32_e32 v0, v0
	v_pk_fma_f32 v[182:183], v[56:57], v[182:183], v[214:215]
	v_lshlrev_b32_e32 v214, 16, v180
	v_cvt_pk_bf16_f32 v179, v182, v183
	v_add_f32_e32 v0, 1.0, v0
	v_rcp_f32_e32 v182, v0
	v_and_b32_e32 v0, 0xffff0000, v184
	v_mul_f32_e32 v0, 0xbfb8aa3b, v0
	v_exp_f32_e32 v0, v0
	v_and_b32_e32 v215, 0xffff0000, v180
	v_lshlrev_b32_e32 v184, 16, v181
	v_add_f32_e32 v0, 1.0, v0
	v_rcp_f32_e32 v183, v0
	v_lshlrev_b32_e32 v0, 16, v185
	v_mul_f32_e32 v0, 0xbfb8aa3b, v0
	v_exp_f32_e32 v0, v0
	v_pk_fma_f32 v[182:183], v[50:51], v[182:183], v[214:215]
	v_add_f32_e32 v0, 1.0, v0
	v_cvt_pk_bf16_f32 v180, v182, v183
	v_rcp_f32_e32 v182, v0
	v_and_b32_e32 v0, 0xffff0000, v185
	v_mul_f32_e32 v0, 0xbfb8aa3b, v0
	v_exp_f32_e32 v0, v0
	v_and_b32_e32 v185, 0xffff0000, v181
	v_add_f32_e32 v0, 1.0, v0
	v_rcp_f32_e32 v183, v0
	s_waitcnt vmcnt(11)
; __device__ __forceinline__ unsigned cvt_pk_bf16(float lo, float hi) { f32x2 v = {lo, hi}; bf16x2_t b = __builtin_convertvector(v, bf16x2_t); return __builtin_bit_cast(unsigned, b); }
; __device__ __forceinline__ float bf_lo(unsigned w) { return __uint_as_float(w << 16); }
; __device__ __forceinline__ float bf_hi(unsigned w) { return __uint_as_float(w & 0xffff0000u); }
; __device__ __forceinline__ float sigm(float v) { return __builtin_amdgcn_rcpf(1.0f + __builtin_amdgcn_exp2f(-1.44269504089f * v)); }
; __device__ __forceinline__ void epi_run(const Epi& E, f32x4 (&acc)[2][2][4][2], const Unit& u, int wr, int wc, int fr, int fq) {
;     ...
;                 for (int bj = 0; bj < 2; ++bj) { const bf16_t* gp = E.Z + (size_t)(row0 + ai * 128 + m * 16) * NIN + 4096 + col0 + bj * 128; g[m][bj] = *(const u32x4*)gp; c[m][bj] = *(const u32x4*)(gp - 1024); }
; #pragma unroll
;             for (int m = 0; m < 4; ++m)
; #pragma unroll
;                 for (int bj = 0; bj < 2; ++bj) { const f32x4 v0 = acc[ai][bj][m][0], v1 = acc[ai][bj][m][1]; const u32x4 gg = g[m][bj], cc = c[m][bj]; u32x4 w;
;                     w.x = cvt_pk_bf16(bf_lo(cc.x) + v0[0] * sigm(bf_lo(gg.x)), bf_hi(cc.x) + v0[1] * sigm(bf_hi(gg.x))); w.y = cvt_pk_bf16(bf_lo(cc.y) + v0[2] * sigm(bf_lo(gg.y)), bf_hi(cc.y) + v0[3] * sigm(bf_hi(gg.y)));
;                     w.z = cvt_pk_bf16(bf_lo(cc.z) + v1[0] * sigm(bf_lo(gg.z)), bf_hi(cc.z) + v1[1] * sigm(bf_hi(gg.z))); w.w = cvt_pk_bf16(bf_lo(cc.w) + v1[2] * sigm(bf_lo(gg.w)), bf_hi(cc.w) + v1[3] * sigm(bf_hi(gg.w)));
;                     *(u32x4*)(E.Z + (size_t)(row0 + ai * 128 + m * 16) * NIN + 4096 + col0 + bj * 128) = w; }
	v_lshlrev_b32_e32 v0, 16, v174
	v_mul_f32_e32 v0, 0xbfb8aa3b, v0
	v_exp_f32_e32 v0, v0
	v_pk_fma_f32 v[182:183], v[52:53], v[182:183], v[184:185]
	v_add_f32_e32 v0, 1.0, v0
	v_cvt_pk_bf16_f32 v181, v182, v183
	s_waitcnt lgkmcnt(0)
	global_store_dwordx4 v[192:193], v[244:247], off
	s_nop 1
	ds_bpermute_b32 v244, v243, v178
	ds_bpermute_b32 v245, v243, v179
	ds_bpermute_b32 v246, v243, v180
	ds_bpermute_b32 v247, v243, v181
	s_nop 1
	v_rcp_f32_e32 v178, v0
	v_and_b32_e32 v0, 0xffff0000, v174
	v_mul_f32_e32 v0, 0xbfb8aa3b, v0
	v_exp_f32_e32 v0, v0
	s_waitcnt vmcnt(11)
	v_lshlrev_b32_e32 v180, 16, v170
	v_and_b32_e32 v181, 0xffff0000, v170
	v_add_f32_e32 v0, 1.0, v0
	v_rcp_f32_e32 v179, v0
	v_lshlrev_b32_e32 v0, 16, v175
	v_mul_f32_e32 v0, 0xbfb8aa3b, v0
	v_exp_f32_e32 v0, v0
	v_pk_fma_f32 v[178:179], v[46:47], v[178:179], v[180:181]
	v_add_f32_e32 v0, 1.0, v0
	v_rcp_f32_e32 v174, v0
	v_and_b32_e32 v0, 0xffff0000, v175
	v_mul_f32_e32 v0, 0xbfb8aa3b, v0
	v_exp_f32_e32 v0, v0
	v_cvt_pk_bf16_f32 v170, v178, v179
	v_lshlrev_b32_e32 v178, 16, v171
	v_and_b32_e32 v179, 0xffff0000, v171
	v_add_f32_e32 v0, 1.0, v0
	v_rcp_f32_e32 v175, v0
	v_lshlrev_b32_e32 v0, 16, v176
	v_mul_f32_e32 v0, 0xbfb8aa3b, v0
	v_exp_f32_e32 v0, v0
	v_pk_fma_f32 v[174:175], v[48:49], v[174:175], v[178:179]
	v_lshlrev_b32_e32 v178, 16, v172
	v_cvt_pk_bf16_f32 v171, v174, v175
	v_add_f32_e32 v0, 1.0, v0
	v_rcp_f32_e32 v174, v0
	v_and_b32_e32 v0, 0xffff0000, v176
	v_mul_f32_e32 v0, 0xbfb8aa3b, v0
	v_exp_f32_e32 v0, v0
	v_and_b32_e32 v179, 0xffff0000, v172
	v_lshlrev_b32_e32 v176, 16, v173
	v_add_f32_e32 v0, 1.0, v0
	v_rcp_f32_e32 v175, v0
	v_lshlrev_b32_e32 v0, 16, v177
	v_mul_f32_e32 v0, 0xbfb8aa3b, v0
	v_exp_f32_e32 v0, v0
	v_pk_fma_f32 v[174:175], v[42:43], v[174:175], v[178:179]
	v_add_f32_e32 v0, 1.0, v0
	v_cvt_pk_bf16_f32 v172, v174, v175
	v_rcp_f32_e32 v174, v0
	v_and_b32_e32 v0, 0xffff0000, v177
	v_mul_f32_e32 v0, 0xbfb8aa3b, v0
	v_exp_f32_e32 v0, v0
	v_and_b32_e32 v177, 0xffff0000, v173
	v_add_f32_e32 v0, 1.0, v0
	v_rcp_f32_e32 v175, v0
	s_waitcnt vmcnt(10)
	v_lshlrev_b32_e32 v0, 16, v166
	v_mul_f32_e32 v0, 0xbfb8aa3b, v0
	v_exp_f32_e32 v0, v0
	v_pk_fma_f32 v[174:175], v[44:45], v[174:175], v[176:177]
	v_add_f32_e32 v0, 1.0, v0
	v_cvt_pk_bf16_f32 v173, v174, v175
	s_waitcnt lgkmcnt(0)
	global_store_dwordx4 v[192:193], v[244:247], off offset:256
	v_lshl_add_u64 v[190:191], v[190:191], 0, v[230:231]
	ds_bpermute_b32 v244, v243, v170
	ds_bpermute_b32 v245, v243, v171
	ds_bpermute_b32 v246, v243, v172
	ds_bpermute_b32 v247, v243, v173
	s_nop 1
	v_rcp_f32_e32 v170, v0
	v_and_b32_e32 v0, 0xffff0000, v166
	v_mul_f32_e32 v0, 0xbfb8aa3b, v0
	v_exp_f32_e32 v0, v0
	s_waitcnt vmcnt(10)
	v_lshlrev_b32_e32 v172, 16, v162
	v_and_b32_e32 v173, 0xffff0000, v162
	v_add_f32_e32 v0, 1.0, v0
	v_rcp_f32_e32 v171, v0
	v_lshlrev_b32_e32 v0, 16, v167
	v_mul_f32_e32 v0, 0xbfb8aa3b, v0
	v_exp_f32_e32 v0, v0
	v_pk_fma_f32 v[170:171], v[38:39], v[170:171], v[172:173]
	v_add_f32_e32 v0, 1.0, v0
	v_rcp_f32_e32 v166, v0
	v_and_b32_e32 v0, 0xffff0000, v167
	v_mul_f32_e32 v0, 0xbfb8aa3b, v0
	v_exp_f32_e32 v0, v0
	v_cvt_pk_bf16_f32 v162, v170, v171
	v_lshlrev_b32_e32 v170, 16, v163
	v_and_b32_e32 v171, 0xffff0000, v163
	v_add_f32_e32 v0, 1.0, v0
	v_rcp_f32_e32 v167, v0
	v_lshlrev_b32_e32 v0, 16, v168
	v_mul_f32_e32 v0, 0xbfb8aa3b, v0
	v_exp_f32_e32 v0, v0
	v_pk_fma_f32 v[166:167], v[40:41], v[166:167], v[170:171]
	v_lshlrev_b32_e32 v170, 16, v164
	v_cvt_pk_bf16_f32 v163, v166, v167
	v_add_f32_e32 v0, 1.0, v0
	v_rcp_f32_e32 v166, v0
	v_and_b32_e32 v0, 0xffff0000, v168
	v_mul_f32_e32 v0, 0xbfb8aa3b, v0
	v_exp_f32_e32 v0, v0
	v_and_b32_e32 v171, 0xffff0000, v164
	v_lshlrev_b32_e32 v168, 16, v165
	v_add_f32_e32 v0, 1.0, v0
	v_rcp_f32_e32 v167, v0
	v_lshlrev_b32_e32 v0, 16, v169
	v_mul_f32_e32 v0, 0xbfb8aa3b, v0
	v_exp_f32_e32 v0, v0
	v_pk_fma_f32 v[166:167], v[34:35], v[166:167], v[170:171]
	v_add_f32_e32 v0, 1.0, v0
	v_cvt_pk_bf16_f32 v164, v166, v167
	v_rcp_f32_e32 v166, v0
	v_and_b32_e32 v0, 0xffff0000, v169
	v_mul_f32_e32 v0, 0xbfb8aa3b, v0
	v_exp_f32_e32 v0, v0
	v_and_b32_e32 v169, 0xffff0000, v165
	v_add_f32_e32 v0, 1.0, v0
	v_rcp_f32_e32 v167, v0
	s_waitcnt vmcnt(9)
	v_lshlrev_b32_e32 v0, 16, v158
	v_mul_f32_e32 v0, 0xbfb8aa3b, v0
	v_exp_f32_e32 v0, v0
	v_pk_fma_f32 v[166:167], v[36:37], v[166:167], v[168:169]
	v_add_f32_e32 v0, 1.0, v0
	v_cvt_pk_bf16_f32 v165, v166, v167
	s_waitcnt lgkmcnt(0)
	global_store_dwordx4 v[190:191], v[244:247], off
	s_nop 1
	ds_bpermute_b32 v244, v243, v162
	ds_bpermute_b32 v245, v243, v163
	ds_bpermute_b32 v246, v243, v164
	ds_bpermute_b32 v247, v243, v165
	s_nop 1
	v_rcp_f32_e32 v162, v0
	v_and_b32_e32 v0, 0xffff0000, v158
	v_mul_f32_e32 v0, 0xbfb8aa3b, v0
	v_exp_f32_e32 v0, v0
	s_waitcnt vmcnt(9)
	v_lshlrev_b32_e32 v164, 16, v154
	v_and_b32_e32 v165, 0xffff0000, v154
	v_add_f32_e32 v0, 1.0, v0
	v_rcp_f32_e32 v163, v0
	v_lshlrev_b32_e32 v0, 16, v159
	v_mul_f32_e32 v0, 0xbfb8aa3b, v0
	v_exp_f32_e32 v0, v0
	v_pk_fma_f32 v[162:163], v[30:31], v[162:163], v[164:165]
	v_add_f32_e32 v0, 1.0, v0
	v_rcp_f32_e32 v158, v0
	v_and_b32_e32 v0, 0xffff0000, v159
	v_mul_f32_e32 v0, 0xbfb8aa3b, v0
	v_exp_f32_e32 v0, v0
	v_cvt_pk_bf16_f32 v154, v162, v163
	v_lshlrev_b32_e32 v162, 16, v155
	v_and_b32_e32 v163, 0xffff0000, v155
	v_add_f32_e32 v0, 1.0, v0
	v_rcp_f32_e32 v159, v0
	v_lshlrev_b32_e32 v0, 16, v160
	v_mul_f32_e32 v0, 0xbfb8aa3b, v0
	v_exp_f32_e32 v0, v0
	v_pk_fma_f32 v[158:159], v[32:33], v[158:159], v[162:163]
	v_lshlrev_b32_e32 v162, 16, v156
	v_cvt_pk_bf16_f32 v155, v158, v159
	v_add_f32_e32 v0, 1.0, v0
	v_rcp_f32_e32 v158, v0
	v_and_b32_e32 v0, 0xffff0000, v160
	v_mul_f32_e32 v0, 0xbfb8aa3b, v0
	v_exp_f32_e32 v0, v0
	v_and_b32_e32 v163, 0xffff0000, v156
	v_lshlrev_b32_e32 v160, 16, v157
	v_add_f32_e32 v0, 1.0, v0
	v_rcp_f32_e32 v159, v0
	v_lshlrev_b32_e32 v0, 16, v161
	v_mul_f32_e32 v0, 0xbfb8aa3b, v0
	v_exp_f32_e32 v0, v0
	v_pk_fma_f32 v[158:159], v[26:27], v[158:159], v[162:163]
	v_add_f32_e32 v0, 1.0, v0
	v_cvt_pk_bf16_f32 v156, v158, v159
	v_rcp_f32_e32 v158, v0
	v_and_b32_e32 v0, 0xffff0000, v161
	v_mul_f32_e32 v0, 0xbfb8aa3b, v0
	v_exp_f32_e32 v0, v0
	v_and_b32_e32 v161, 0xffff0000, v157
	v_add_f32_e32 v0, 1.0, v0
	v_rcp_f32_e32 v159, v0
	s_waitcnt vmcnt(8)
; __device__ __forceinline__ unsigned cvt_pk_bf16(float lo, float hi) { f32x2 v = {lo, hi}; bf16x2_t b = __builtin_convertvector(v, bf16x2_t); return __builtin_bit_cast(unsigned, b); }
; __device__ __forceinline__ float bf_lo(unsigned w) { return __uint_as_float(w << 16); }
; __device__ __forceinline__ float bf_hi(unsigned w) { return __uint_as_float(w & 0xffff0000u); }
; __device__ __forceinline__ float sigm(float v) { return __builtin_amdgcn_rcpf(1.0f + __builtin_amdgcn_exp2f(-1.44269504089f * v)); }
; __device__ __forceinline__ void epi_run(const Epi& E, f32x4 (&acc)[2][2][4][2], const Unit& u, int wr, int wc, int fr, int fq) {
;     ...
;                 for (int bj = 0; bj < 2; ++bj) { const bf16_t* gp = E.Z + (size_t)(row0 + ai * 128 + m * 16) * NIN + 4096 + col0 + bj * 128; g[m][bj] = *(const u32x4*)gp; c[m][bj] = *(const u32x4*)(gp - 1024); }
; #pragma unroll
;             for (int m = 0; m < 4; ++m)
; #pragma unroll
;                 for (int bj = 0; bj < 2; ++bj) { const f32x4 v0 = acc[ai][bj][m][0], v1 = acc[ai][bj][m][1]; const u32x4 gg = g[m][bj], cc = c[m][bj]; u32x4 w;
;                     w.x = cvt_pk_bf16(bf_lo(cc.x) + v0[0] * sigm(bf_lo(gg.x)), bf_hi(cc.x) + v0[1] * sigm(bf_hi(gg.x))); w.y = cvt_pk_bf16(bf_lo(cc.y) + v0[2] * sigm(bf_lo(gg.y)), bf_hi(cc.y) + v0[3] * sigm(bf_hi(gg.y)));
;                     w.z = cvt_pk_bf16(bf_lo(cc.z) + v1[0] * sigm(bf_lo(gg.z)), bf_hi(cc.z) + v1[1] * sigm(bf_hi(gg.z))); w.w = cvt_pk_bf16(bf_lo(cc.w) + v1[2] * sigm(bf_lo(gg.w)), bf_hi(cc.w) + v1[3] * sigm(bf_hi(gg.w)));
;                     *(u32x4*)(E.Z + (size_t)(row0 + ai * 128 + m * 16) * NIN + 4096 + col0 + bj * 128) = w; }
	v_lshlrev_b32_e32 v0, 16, v150
	v_mul_f32_e32 v0, 0xbfb8aa3b, v0
	v_exp_f32_e32 v0, v0
	v_pk_fma_f32 v[158:159], v[28:29], v[158:159], v[160:161]
	v_add_f32_e32 v0, 1.0, v0
	v_cvt_pk_bf16_f32 v157, v158, v159
	s_waitcnt lgkmcnt(0)
	global_store_dwordx4 v[190:191], v[244:247], off offset:256
	v_lshl_add_u64 v[188:189], v[188:189], 0, v[230:231]
	ds_bpermute_b32 v244, v243, v154
	ds_bpermute_b32 v245, v243, v155
	ds_bpermute_b32 v246, v243, v156
	ds_bpermute_b32 v247, v243, v157
	s_nop 1
	v_rcp_f32_e32 v154, v0
	v_and_b32_e32 v0, 0xffff0000, v150
	v_mul_f32_e32 v0, 0xbfb8aa3b, v0
	v_exp_f32_e32 v0, v0
	s_waitcnt vmcnt(8)
	v_lshlrev_b32_e32 v156, 16, v146
	v_and_b32_e32 v157, 0xffff0000, v146
	v_add_f32_e32 v0, 1.0, v0
	v_rcp_f32_e32 v155, v0
	v_lshlrev_b32_e32 v0, 16, v151
	v_mul_f32_e32 v0, 0xbfb8aa3b, v0
	v_exp_f32_e32 v0, v0
	v_pk_fma_f32 v[154:155], v[22:23], v[154:155], v[156:157]
	v_add_f32_e32 v0, 1.0, v0
	v_rcp_f32_e32 v150, v0
	v_and_b32_e32 v0, 0xffff0000, v151
	v_mul_f32_e32 v0, 0xbfb8aa3b, v0
	v_exp_f32_e32 v0, v0
	v_cvt_pk_bf16_f32 v146, v154, v155
	v_lshlrev_b32_e32 v154, 16, v147
	v_and_b32_e32 v155, 0xffff0000, v147
	v_add_f32_e32 v0, 1.0, v0
	v_rcp_f32_e32 v151, v0
	v_lshlrev_b32_e32 v0, 16, v152
	v_mul_f32_e32 v0, 0xbfb8aa3b, v0
	v_exp_f32_e32 v0, v0
	v_pk_fma_f32 v[150:151], v[24:25], v[150:151], v[154:155]
	v_lshlrev_b32_e32 v154, 16, v148
	v_cvt_pk_bf16_f32 v147, v150, v151
	v_add_f32_e32 v0, 1.0, v0
	v_rcp_f32_e32 v150, v0
	v_and_b32_e32 v0, 0xffff0000, v152
	v_mul_f32_e32 v0, 0xbfb8aa3b, v0
	v_exp_f32_e32 v0, v0
	v_and_b32_e32 v155, 0xffff0000, v148
	v_lshlrev_b32_e32 v152, 16, v149
	v_add_f32_e32 v0, 1.0, v0
	v_rcp_f32_e32 v151, v0
	v_lshlrev_b32_e32 v0, 16, v153
	v_mul_f32_e32 v0, 0xbfb8aa3b, v0
	v_exp_f32_e32 v0, v0
	v_pk_fma_f32 v[150:151], v[18:19], v[150:151], v[154:155]
	v_add_f32_e32 v0, 1.0, v0
	v_cvt_pk_bf16_f32 v148, v150, v151
	v_rcp_f32_e32 v150, v0
	v_and_b32_e32 v0, 0xffff0000, v153
	v_mul_f32_e32 v0, 0xbfb8aa3b, v0
	v_exp_f32_e32 v0, v0
	v_and_b32_e32 v153, 0xffff0000, v149
	v_add_f32_e32 v0, 1.0, v0
	v_rcp_f32_e32 v151, v0
	s_waitcnt vmcnt(7)
	v_lshlrev_b32_e32 v0, 16, v142
	v_mul_f32_e32 v0, 0xbfb8aa3b, v0
	v_exp_f32_e32 v0, v0
	v_pk_fma_f32 v[150:151], v[20:21], v[150:151], v[152:153]
	v_add_f32_e32 v0, 1.0, v0
	v_cvt_pk_bf16_f32 v149, v150, v151
	s_waitcnt lgkmcnt(0)
	global_store_dwordx4 v[188:189], v[244:247], off
	s_nop 1
	ds_bpermute_b32 v244, v243, v146
	ds_bpermute_b32 v245, v243, v147
	ds_bpermute_b32 v246, v243, v148
	ds_bpermute_b32 v247, v243, v149
	s_nop 1
	v_rcp_f32_e32 v146, v0
	v_and_b32_e32 v0, 0xffff0000, v142
	v_mul_f32_e32 v0, 0xbfb8aa3b, v0
	v_exp_f32_e32 v0, v0
	s_waitcnt vmcnt(7)
	v_lshlrev_b32_e32 v148, 16, v138
	v_and_b32_e32 v149, 0xffff0000, v138
	v_add_f32_e32 v0, 1.0, v0
	v_rcp_f32_e32 v147, v0
	v_lshlrev_b32_e32 v0, 16, v143
	v_mul_f32_e32 v0, 0xbfb8aa3b, v0
	v_exp_f32_e32 v0, v0
	v_pk_fma_f32 v[146:147], v[14:15], v[146:147], v[148:149]
	v_add_f32_e32 v0, 1.0, v0
	v_rcp_f32_e32 v142, v0
	v_and_b32_e32 v0, 0xffff0000, v143
	v_mul_f32_e32 v0, 0xbfb8aa3b, v0
	v_exp_f32_e32 v0, v0
	v_cvt_pk_bf16_f32 v138, v146, v147
	v_lshlrev_b32_e32 v146, 16, v139
	v_and_b32_e32 v147, 0xffff0000, v139
	v_add_f32_e32 v0, 1.0, v0
	v_rcp_f32_e32 v143, v0
	v_lshlrev_b32_e32 v0, 16, v144
	v_mul_f32_e32 v0, 0xbfb8aa3b, v0
	v_exp_f32_e32 v0, v0
	v_pk_fma_f32 v[142:143], v[16:17], v[142:143], v[146:147]
	v_lshlrev_b32_e32 v146, 16, v140
	v_cvt_pk_bf16_f32 v139, v142, v143
	v_add_f32_e32 v0, 1.0, v0
	v_rcp_f32_e32 v142, v0
	v_and_b32_e32 v0, 0xffff0000, v144
	v_mul_f32_e32 v0, 0xbfb8aa3b, v0
	v_exp_f32_e32 v0, v0
	v_and_b32_e32 v147, 0xffff0000, v140
	v_lshlrev_b32_e32 v144, 16, v141
	v_add_f32_e32 v0, 1.0, v0
	v_rcp_f32_e32 v143, v0
	v_lshlrev_b32_e32 v0, 16, v145
	v_mul_f32_e32 v0, 0xbfb8aa3b, v0
	v_exp_f32_e32 v0, v0
	v_pk_fma_f32 v[142:143], v[10:11], v[142:143], v[146:147]
	v_add_f32_e32 v0, 1.0, v0
	v_cvt_pk_bf16_f32 v140, v142, v143
	v_rcp_f32_e32 v142, v0
	v_and_b32_e32 v0, 0xffff0000, v145
	v_mul_f32_e32 v0, 0xbfb8aa3b, v0
	v_exp_f32_e32 v0, v0
	v_and_b32_e32 v145, 0xffff0000, v141
	v_add_f32_e32 v0, 1.0, v0
	v_rcp_f32_e32 v143, v0
	s_waitcnt vmcnt(6)
	v_lshlrev_b32_e32 v0, 16, v134
	v_mul_f32_e32 v0, 0xbfb8aa3b, v0
	v_exp_f32_e32 v0, v0
	v_pk_fma_f32 v[142:143], v[12:13], v[142:143], v[144:145]
	v_add_f32_e32 v0, 1.0, v0
	v_cvt_pk_bf16_f32 v141, v142, v143
	s_waitcnt lgkmcnt(0)
	global_store_dwordx4 v[188:189], v[244:247], off offset:256
	v_lshl_add_u64 v[186:187], v[186:187], 0, v[230:231]
	ds_bpermute_b32 v244, v243, v138
	ds_bpermute_b32 v245, v243, v139
	ds_bpermute_b32 v246, v243, v140
	ds_bpermute_b32 v247, v243, v141
	s_nop 1
	v_rcp_f32_e32 v138, v0
	v_and_b32_e32 v0, 0xffff0000, v134
	v_mul_f32_e32 v0, 0xbfb8aa3b, v0
	v_exp_f32_e32 v0, v0
	s_waitcnt vmcnt(6)
	v_lshlrev_b32_e32 v140, 16, v130
	v_and_b32_e32 v141, 0xffff0000, v130
	v_add_f32_e32 v0, 1.0, v0
	v_rcp_f32_e32 v139, v0
	v_lshlrev_b32_e32 v0, 16, v135
	v_mul_f32_e32 v0, 0xbfb8aa3b, v0
	v_exp_f32_e32 v0, v0
	v_pk_fma_f32 v[138:139], v[6:7], v[138:139], v[140:141]
	v_add_f32_e32 v0, 1.0, v0
	v_rcp_f32_e32 v134, v0
	v_and_b32_e32 v0, 0xffff0000, v135
	v_mul_f32_e32 v0, 0xbfb8aa3b, v0
	v_exp_f32_e32 v0, v0
	v_cvt_pk_bf16_f32 v130, v138, v139
	v_lshlrev_b32_e32 v138, 16, v131
	v_and_b32_e32 v139, 0xffff0000, v131
	v_add_f32_e32 v0, 1.0, v0
	v_rcp_f32_e32 v135, v0
	v_lshlrev_b32_e32 v0, 16, v136
	v_mul_f32_e32 v0, 0xbfb8aa3b, v0
	v_exp_f32_e32 v0, v0
	v_pk_fma_f32 v[134:135], v[8:9], v[134:135], v[138:139]
	v_lshlrev_b32_e32 v138, 16, v132
	v_cvt_pk_bf16_f32 v131, v134, v135
	v_add_f32_e32 v0, 1.0, v0
	v_rcp_f32_e32 v134, v0
	v_and_b32_e32 v0, 0xffff0000, v136
	v_mul_f32_e32 v0, 0xbfb8aa3b, v0
	v_exp_f32_e32 v0, v0
	v_and_b32_e32 v139, 0xffff0000, v132
	v_lshlrev_b32_e32 v136, 16, v133
	v_add_f32_e32 v0, 1.0, v0
	v_rcp_f32_e32 v135, v0
	v_lshlrev_b32_e32 v0, 16, v137
	v_mul_f32_e32 v0, 0xbfb8aa3b, v0
	v_exp_f32_e32 v0, v0
	v_pk_fma_f32 v[134:135], v[2:3], v[134:135], v[138:139]
	v_add_f32_e32 v0, 1.0, v0
	v_cvt_pk_bf16_f32 v132, v134, v135
	v_rcp_f32_e32 v134, v0
	v_and_b32_e32 v0, 0xffff0000, v137
	v_mul_f32_e32 v0, 0xbfb8aa3b, v0
	v_exp_f32_e32 v0, v0
	v_and_b32_e32 v137, 0xffff0000, v133
	v_add_f32_e32 v0, 1.0, v0
	v_rcp_f32_e32 v135, v0
	s_nop 0
	v_pk_fma_f32 v[134:135], v[4:5], v[134:135], v[136:137]
	s_nop 0
	v_cvt_pk_bf16_f32 v133, v134, v135
	s_waitcnt lgkmcnt(0)
	global_store_dwordx4 v[186:187], v[244:247], off
	s_nop 1
	ds_bpermute_b32 v244, v243, v130
	ds_bpermute_b32 v245, v243, v131
	ds_bpermute_b32 v246, v243, v132
	ds_bpermute_b32 v247, v243, v133
	s_waitcnt lgkmcnt(0)
	global_store_dwordx4 v[186:187], v[244:247], off offset:256
	s_branch .LBB0_299

; __device__ __forceinline__ float bf_lo(unsigned w) { return __uint_as_float(w << 16); }
; __device__ __forceinline__ float bf_hi(unsigned w) { return __uint_as_float(w & 0xffff0000u); }
; __device__ __forceinline__ float sigm(float v) { return __builtin_amdgcn_rcpf(1.0f + __builtin_amdgcn_exp2f(-1.44269504089f * v)); }
; __device__ __forceinline__ u32x4 pack8(const f32x4& v0, const f32x4& v1) { u32x4 w; w.x = cvt_pk_bf16(v0[0], v0[1]); w.y = cvt_pk_bf16(v0[2], v0[3]); w.z = cvt_pk_bf16(v1[0], v1[1]); w.w = cvt_pk_bf16(v1[2], v1[3]); return w; }
; __device__ __forceinline__ float sumsq8(const f32x4& v0, const f32x4& v1) { return (v0[0] * v0[0] + v0[1] * v0[1]) + (v0[2] * v0[2] + v0[3] * v0[3]) + (v1[0] * v1[0] + v1[1] * v1[1]) + (v1[2] * v1[2] + v1[3] * v1[3]); }
; __device__ __forceinline__ void epi_run(const Epi& E, f32x4 (&acc)[2][2][4][2], const Unit& u, int wr, int wc, int fr, int fq) {
;     ...
;                 for (int mm = 0; mm < 2; ++mm) { const int m = 2 * mh + mm, row = row0 + ai * 128 + m * 16; float sq = 0.f;
; #pragma unroll
;                     for (int bj = 0; bj < 2; ++bj) { const u32x4 xx = x[mm][bj], cc = c[mm][bj];
;                         const f32x4 c0 = (f32x4){bf_lo(cc.x), bf_hi(cc.x), bf_lo(cc.y), bf_hi(cc.y)}, c1 = (f32x4){bf_lo(cc.z), bf_hi(cc.z), bf_lo(cc.w), bf_hi(cc.w)};
;                         f32x4 v0 = acc[ai][bj][m][0] * rs[ai][m], v1 = acc[ai][bj][m][1] * rs[ai][m];
; #pragma unroll
;                         for (int e = 0; e < 4; ++e) { v0[e] = sigm(v0[e]) * c0[e]; v1[e] = sigm(v1[e]) * c1[e]; }
;                         const f32x4 x0 = (f32x4){bf_lo(xx.x), bf_hi(xx.x), bf_lo(xx.y), bf_hi(xx.y)} + v0, x1 = (f32x4){bf_lo(xx.z), bf_hi(xx.z), bf_lo(xx.w), bf_hi(xx.w)} + v1;
;                         sq += sumsq8(x0, x1); *(u32x4*)(E.xout16 + (size_t)row * D + col0 + bj * 128) = pack8(x0, x1); }
;                     sq += __shfl_xor(sq, 16); sq += __shfl_xor(sq, 32); if (fq == 0) sslot[row] = sq; }
.LBB0_311:
	s_or_b64 exec, exec, s[8:9]
	v_add_f32_e32 v148, v151, v152
	v_fmamk_f32 v148, v148, 0x3a800000, v197
	v_rsq_f32_e32 v148, v148
	s_waitcnt vmcnt(2)
	v_lshlrev_b32_e32 v160, 16, v142
	v_and_b32_e32 v161, 0xffff0000, v142
	v_lshlrev_b32_e32 v162, 16, v144
	s_waitcnt lgkmcnt(0)
	v_pk_mul_f32 v[154:155], v[110:111], v[148:149] op_sel_hi:[1,0]
	v_pk_mul_f32 v[152:153], v[112:113], v[148:149] op_sel_hi:[1,0]
	v_pk_mul_f32 v[156:157], v[108:109], v[148:149] op_sel_hi:[1,0]
	v_mul_f32_e32 v149, 0xbfb8aa3b, v154
	v_exp_f32_e32 v149, v149
	v_mul_f32_e32 v154, 0xbfb8aa3b, v155
	v_exp_f32_e32 v155, v154
	v_and_b32_e32 v163, 0xffff0000, v144
	v_pk_mul_f32 v[158:159], v[106:107], v[148:149] op_sel_hi:[1,0]
	v_add_f32_e32 v149, 1.0, v149
	v_mul_f32_e32 v151, 0xbfb8aa3b, v158
	v_exp_f32_e32 v151, v151
	v_rcp_f32_e32 v154, v149
	v_mul_f32_e32 v144, 0xbfb8aa3b, v156
	v_exp_f32_e32 v144, v144
	v_add_f32_e32 v149, 1.0, v151
	v_rcp_f32_e32 v158, v149
	v_add_f32_e32 v149, 1.0, v155
	v_mul_f32_e32 v151, 0xbfb8aa3b, v159
	v_exp_f32_e32 v151, v151
	v_rcp_f32_e32 v155, v149
	v_mul_f32_e32 v149, 0xbfb8aa3b, v152
	v_exp_f32_e32 v149, v149
	v_add_f32_e32 v142, 1.0, v151
	v_rcp_f32_e32 v159, v142
	v_lshlrev_b32_e32 v156, 16, v143
	v_add_f32_e32 v142, 1.0, v149
	v_mul_f32_e32 v149, 0xbfb8aa3b, v153
	v_exp_f32_e32 v149, v149
	v_rcp_f32_e32 v152, v142
	v_add_f32_e32 v142, 1.0, v144
	v_rcp_f32_e32 v142, v142
	v_add_f32_e32 v144, 1.0, v149
	v_mul_f32_e32 v149, 0xbfb8aa3b, v157
	v_exp_f32_e32 v149, v149
	v_rcp_f32_e32 v153, v144
	v_and_b32_e32 v157, 0xffff0000, v143
	v_lshlrev_b32_e32 v164, 16, v138
	v_add_f32_e32 v143, 1.0, v149
	v_rcp_f32_e32 v143, v143
	v_and_b32_e32 v165, 0xffff0000, v138
	v_lshlrev_b32_e32 v138, 16, v139
	v_and_b32_e32 v139, 0xffff0000, v139
	v_lshlrev_b32_e32 v144, 16, v145
	v_and_b32_e32 v145, 0xffff0000, v145
	v_pk_fma_f32 v[152:153], v[152:153], v[156:157], v[138:139]
	v_pk_fma_f32 v[138:139], v[154:155], v[160:161], v[164:165]
	v_lshlrev_b32_e32 v154, 16, v140
	v_and_b32_e32 v155, 0xffff0000, v140
	v_lshlrev_b32_e32 v140, 16, v141
	v_and_b32_e32 v141, 0xffff0000, v141
	v_pk_fma_f32 v[142:143], v[142:143], v[144:145], v[140:141]
	v_mul_f32_e32 v144, v139, v139
	v_mul_f32_e32 v145, v153, v153
	v_pk_fma_f32 v[140:141], v[158:159], v[162:163], v[154:155]
	v_fmac_f32_e32 v144, v138, v138
	v_fmac_f32_e32 v145, v152, v152
	v_add_f32_e32 v144, v144, v145
	v_mul_f32_e32 v145, v141, v141
	v_fmac_f32_e32 v145, v140, v140
	v_add_f32_e32 v144, v145, v144
	v_mul_f32_e32 v145, v143, v143
	v_fmac_f32_e32 v145, v142, v142
	v_add_f32_e32 v151, v145, v144
	v_cvt_pk_bf16_f32 v138, v138, v139
	v_cvt_pk_bf16_f32 v139, v152, v153
	v_cvt_pk_bf16_f32 v140, v140, v141
	v_cvt_pk_bf16_f32 v141, v142, v143
	v_pk_mul_f32 v[142:143], v[102:103], v[148:149] op_sel_hi:[1,0]
	v_pk_mul_f32 v[144:145], v[104:105], v[148:149] op_sel_hi:[1,0]
	v_pk_mul_f32 v[152:153], v[96:97], v[148:149] op_sel_hi:[1,0]
	v_pk_mul_f32 v[148:149], v[94:95], v[148:149] op_sel_hi:[1,0]
	v_mul_f32_e32 v144, 0xbfb8aa3b, v144
	v_mul_f32_e32 v149, 0xbfb8aa3b, v149
	v_exp_f32_e32 v149, v149
	v_exp_f32_e32 v144, v144
	s_waitcnt vmcnt(1)
	v_lshlrev_b32_e32 v154, 16, v134
	v_and_b32_e32 v155, 0xffff0000, v134
	v_add_f32_e32 v134, 1.0, v149
	v_rcp_f32_e32 v149, v134
	v_lshlrev_b32_e32 v156, 16, v136
	v_and_b32_e32 v157, 0xffff0000, v136
	v_add_f32_e32 v134, 1.0, v144
	v_mul_f32_e32 v136, 0xbfb8aa3b, v152
	v_mul_f32_e32 v144, 0xbfb8aa3b, v145
	v_exp_f32_e32 v136, v136
	v_exp_f32_e32 v145, v144
	v_mul_f32_e32 v142, 0xbfb8aa3b, v142
	v_mul_f32_e32 v143, 0xbfb8aa3b, v143
	v_exp_f32_e32 v142, v142
	v_exp_f32_e32 v143, v143
	v_rcp_f32_e32 v144, v134
	v_add_f32_e32 v134, 1.0, v136
	v_add_f32_e32 v136, 1.0, v145
	v_mul_f32_e32 v145, 0xbfb8aa3b, v153
	v_mul_f32_e32 v148, 0xbfb8aa3b, v148
	v_exp_f32_e32 v158, v145
	v_exp_f32_e32 v148, v148
	v_add_f32_e32 v142, 1.0, v142
	v_add_f32_e32 v143, 1.0, v143
	v_rcp_f32_e32 v142, v142
	v_rcp_f32_e32 v143, v143
	v_rcp_f32_e32 v145, v136
	v_lshlrev_b32_e32 v152, 16, v135
	v_and_b32_e32 v153, 0xffff0000, v135
	v_add_f32_e32 v135, 1.0, v158
	v_add_f32_e32 v148, 1.0, v148
	v_rcp_f32_e32 v134, v134
	v_rcp_f32_e32 v135, v135
	v_rcp_f32_e32 v148, v148
	v_lshlrev_b32_e32 v158, 16, v130
	v_and_b32_e32 v159, 0xffff0000, v130
	v_lshlrev_b32_e32 v130, 16, v131
	v_and_b32_e32 v131, 0xffff0000, v131
	v_lshlrev_b32_e32 v136, 16, v137
	v_and_b32_e32 v137, 0xffff0000, v137
	v_pk_fma_f32 v[144:145], v[144:145], v[152:153], v[130:131]
	v_pk_fma_f32 v[130:131], v[142:143], v[154:155], v[158:159]
	v_lshlrev_b32_e32 v142, 16, v132
	v_and_b32_e32 v143, 0xffff0000, v132
	v_lshlrev_b32_e32 v132, 16, v133
	v_and_b32_e32 v133, 0xffff0000, v133
	v_pk_fma_f32 v[136:137], v[134:135], v[136:137], v[132:133]
	v_mul_f32_e32 v132, v131, v131
	v_mul_f32_e32 v133, v145, v145
	v_pk_fma_f32 v[134:135], v[148:149], v[156:157], v[142:143]
	v_fmac_f32_e32 v132, v130, v130
	v_fmac_f32_e32 v133, v144, v144
	v_add_f32_e32 v132, v132, v133
	v_mul_f32_e32 v133, v135, v135
	v_fmac_f32_e32 v133, v134, v134
	v_add_f32_e32 v132, v133, v132
	v_mul_f32_e32 v133, v137, v137
	v_fmac_f32_e32 v133, v136, v136
	v_add_f32_e32 v132, v133, v132
	v_add_f32_e32 v148, v151, v132
	ds_bpermute_b32 v149, v171, v148
	v_lshlrev_b64 v[146:147], 11, v[146:147]
	v_lshl_add_u64 v[132:133], s[78:79], 0, v[146:147]
	v_lshl_add_u64 v[142:143], v[212:213], 1, v[132:133]
	v_cvt_pk_bf16_f32 v132, v130, v131
	s_waitcnt lgkmcnt(0)
	v_add_f32_e32 v130, v148, v149
	ds_bpermute_b32 v131, v170, v130
	v_cvt_pk_bf16_f32 v133, v144, v145
	v_cvt_pk_bf16_f32 v134, v134, v135
	v_cvt_pk_bf16_f32 v135, v136, v137
	s_waitcnt lgkmcnt(0)
	global_store_dwordx4 v[228:229], v[222:225], off offset:256
	v_lshl_add_u64 v[226:227], v[142:143], 0, v[230:231]
	ds_bpermute_b32 v218, v243, v138
	ds_bpermute_b32 v219, v243, v139
	ds_bpermute_b32 v220, v243, v140
	ds_bpermute_b32 v221, v243, v141
	s_waitcnt lgkmcnt(0)
	global_store_dwordx4 v[226:227], v[218:221], off
	v_lshl_add_u64 v[228:229], v[142:143], 0, v[230:231]
	ds_bpermute_b32 v222, v243, v132
	ds_bpermute_b32 v223, v243, v133
	ds_bpermute_b32 v224, v243, v134
	ds_bpermute_b32 v225, v243, v135
	s_and_saveexec_b64 s[8:9], s[40:41]
	s_cbranch_execz .LBB0_313
	v_lshl_add_u64 v[132:133], v[210:211], 2, s[44:45]
	s_waitcnt lgkmcnt(0)
	v_add_f32_e32 v130, v130, v131
	global_store_dword v[132:133], v130, off offset:64
; __device__ __forceinline__ float bf_lo(unsigned w) { return __uint_as_float(w << 16); }
; __device__ __forceinline__ float bf_hi(unsigned w) { return __uint_as_float(w & 0xffff0000u); }
; __device__ __forceinline__ float sigm(float v) { return __builtin_amdgcn_rcpf(1.0f + __builtin_amdgcn_exp2f(-1.44269504089f * v)); }
; __device__ __forceinline__ u32x4 pack8(const f32x4& v0, const f32x4& v1) { u32x4 w; w.x = cvt_pk_bf16(v0[0], v0[1]); w.y = cvt_pk_bf16(v0[2], v0[3]); w.z = cvt_pk_bf16(v1[0], v1[1]); w.w = cvt_pk_bf16(v1[2], v1[3]); return w; }
; __device__ __forceinline__ float sumsq8(const f32x4& v0, const f32x4& v1) { return (v0[0] * v0[0] + v0[1] * v0[1]) + (v0[2] * v0[2] + v0[3] * v0[3]) + (v1[0] * v1[0] + v1[1] * v1[1]) + (v1[2] * v1[2] + v1[3] * v1[3]); }
; __device__ __forceinline__ void epi_run(const Epi& E, f32x4 (&acc)[2][2][4][2], const Unit& u, int wr, int wc, int fr, int fq) {
;     ...
;             for (int mh = 0; mh < 2; ++mh) { u32x4 x[2][2], c[2][2];
; #pragma unroll
;                 for (int mm = 0; mm < 2; ++mm)
; #pragma unroll
;                     for (int bj = 0; bj < 2; ++bj) { const size_t off = (size_t)(row0 + ai * 128 + (2 * mh + mm) * 16) * D + col0 + bj * 128; x[mm][bj] = *(const u32x4*)(E.xin16 + off); c[mm][bj] = *(const u32x4*)(E.C16 + off); }
; #pragma unroll
;                 for (int mm = 0; mm < 2; ++mm) { const int m = 2 * mh + mm, row = row0 + ai * 128 + m * 16; float sq = 0.f;
; #pragma unroll
;                     for (int bj = 0; bj < 2; ++bj) { const u32x4 xx = x[mm][bj], cc = c[mm][bj];
;                         const f32x4 c0 = (f32x4){bf_lo(cc.x), bf_hi(cc.x), bf_lo(cc.y), bf_hi(cc.y)}, c1 = (f32x4){bf_lo(cc.z), bf_hi(cc.z), bf_lo(cc.w), bf_hi(cc.w)};
;                         f32x4 v0 = acc[ai][bj][m][0] * rs[ai][m], v1 = acc[ai][bj][m][1] * rs[ai][m];
; #pragma unroll
;                         for (int e = 0; e < 4; ++e) { v0[e] = sigm(v0[e]) * c0[e]; v1[e] = sigm(v1[e]) * c1[e]; }
;                         const f32x4 x0 = (f32x4){bf_lo(xx.x), bf_hi(xx.x), bf_lo(xx.y), bf_hi(xx.y)} + v0, x1 = (f32x4){bf_lo(xx.z), bf_hi(xx.z), bf_lo(xx.w), bf_hi(xx.w)} + v1;
;                         sq += sumsq8(x0, x1); *(u32x4*)(E.xout16 + (size_t)row * D + col0 + bj * 128) = pack8(x0, x1); }
;                     sq += __shfl_xor(sq, 16); sq += __shfl_xor(sq, 32); if (fq == 0) sslot[row] = sq; }
.LBB0_313:
	s_or_b64 exec, exec, s[8:9]
	v_or_b32_e32 v164, 32, v210
	v_ashrrev_i32_e32 v165, 31, v164
	s_waitcnt lgkmcnt(0)
	v_lshlrev_b64 v[130:131], 10, v[164:165]
	v_lshl_add_u64 v[130:131], v[130:131], 0, v[212:213]
	v_lshlrev_b64 v[130:131], 1, v[130:131]
	v_lshl_add_u64 v[132:133], s[48:49], 0, v[130:131]
	v_lshl_add_u64 v[134:135], s[62:63], 0, v[130:131]
	global_load_dwordx4 v[154:157], v[132:133], off
	global_load_dwordx4 v[158:161], v[134:135], off
	global_load_dwordx4 v[146:149], v[132:133], off offset:256
	v_or_b32_e32 v130, 0x100, v130
	v_lshl_add_u64 v[130:131], s[62:63], 0, v[130:131]
	v_add_f32_e32 v0, v0, v150
	global_load_dwordx4 v[150:153], v[130:131], off
	v_fmamk_f32 v0, v0, 0x3a800000, v197
	v_rsq_f32_e32 v0, v0
	v_or_b32_e32 v162, 48, v210
	v_ashrrev_i32_e32 v163, 31, v162
	v_lshlrev_b64 v[130:131], 10, v[162:163]
	v_pk_mul_f32 v[166:167], v[98:99], v[0:1] op_sel_hi:[1,0]
	v_pk_mul_f32 v[186:187], v[90:91], v[0:1] op_sel_hi:[1,0]
	v_mul_f32_e32 v167, 0xbfb8aa3b, v167
	v_exp_f32_e32 v167, v167
	v_pk_mul_f32 v[182:183], v[100:101], v[0:1] op_sel_hi:[1,0]
	v_mul_f32_e32 v166, 0xbfb8aa3b, v166
	v_exp_f32_e32 v166, v166
	v_add_f32_e32 v167, 1.0, v167
	v_rcp_f32_e32 v169, v167
	v_pk_mul_f32 v[184:185], v[92:93], v[0:1] op_sel_hi:[1,0]
	v_add_f32_e32 v166, 1.0, v166
	v_rcp_f32_e32 v168, v166
	v_mul_f32_e32 v166, 0xbfb8aa3b, v186
	v_exp_f32_e32 v166, v166
	v_lshl_add_u64 v[130:131], v[130:131], 0, v[212:213]
	v_lshlrev_b64 v[134:135], 1, v[130:131]
	v_lshl_add_u64 v[130:131], s[48:49], 0, v[134:135]
	v_add_f32_e32 v166, 1.0, v166
	v_rcp_f32_e32 v166, v166
	v_lshl_add_u64 v[132:133], s[62:63], 0, v[134:135]
	v_or_b32_e32 v134, 0x100, v134
	v_lshl_add_u64 v[134:135], s[62:63], 0, v[134:135]
	global_load_dwordx4 v[138:141], v[130:131], off
	global_load_dwordx4 v[142:145], v[132:133], off
	s_nop 0
	global_load_dwordx4 v[130:133], v[130:131], off offset:256
	v_lshlrev_b64 v[164:165], 11, v[164:165]
	global_load_dwordx4 v[134:137], v[134:135], off
	s_waitcnt vmcnt(6)
	v_lshlrev_b32_e32 v188, 16, v158
	v_and_b32_e32 v189, 0xffff0000, v158
	v_mul_f32_e32 v158, 0xbfb8aa3b, v187
	v_exp_f32_e32 v158, v158
	v_lshlrev_b32_e32 v186, 16, v160
	v_and_b32_e32 v187, 0xffff0000, v160
	v_mul_f32_e32 v160, 0xbfb8aa3b, v183
	v_add_f32_e32 v158, 1.0, v158
	v_rcp_f32_e32 v167, v158
	v_mul_f32_e32 v158, 0xbfb8aa3b, v182
	v_exp_f32_e32 v158, v158
	v_exp_f32_e32 v160, v160
	v_lshlrev_b32_e32 v190, 16, v159
	v_and_b32_e32 v191, 0xffff0000, v159
	v_add_f32_e32 v158, 1.0, v158
	v_rcp_f32_e32 v182, v158
	v_mul_f32_e32 v158, 0xbfb8aa3b, v184
	v_mul_f32_e32 v159, 0xbfb8aa3b, v185
	v_exp_f32_e32 v158, v158
	v_exp_f32_e32 v159, v159
	v_add_f32_e32 v160, 1.0, v160
	v_rcp_f32_e32 v183, v160
	v_add_f32_e32 v158, 1.0, v158
	v_add_f32_e32 v159, 1.0, v159
	v_rcp_f32_e32 v158, v158
	v_rcp_f32_e32 v159, v159
	v_lshlrev_b32_e32 v184, 16, v154
	v_and_b32_e32 v185, 0xffff0000, v154
	v_lshlrev_b32_e32 v154, 16, v155
	v_and_b32_e32 v155, 0xffff0000, v155
	v_lshlrev_b32_e32 v160, 16, v161
	v_and_b32_e32 v161, 0xffff0000, v161
	v_pk_fma_f32 v[154:155], v[182:183], v[190:191], v[154:155]
	v_pk_fma_f32 v[168:169], v[168:169], v[188:189], v[184:185]
	v_lshlrev_b32_e32 v182, 16, v156
	v_and_b32_e32 v183, 0xffff0000, v156
	v_lshlrev_b32_e32 v156, 16, v157
	v_and_b32_e32 v157, 0xffff0000, v157
	v_pk_fma_f32 v[160:161], v[158:159], v[160:161], v[156:157]
	v_mul_f32_e32 v156, v169, v169
	v_mul_f32_e32 v157, v155, v155
	v_pk_fma_f32 v[158:159], v[166:167], v[186:187], v[182:183]
	v_fmac_f32_e32 v156, v168, v168
	v_fmac_f32_e32 v157, v154, v154
	v_add_f32_e32 v156, v156, v157
	v_mul_f32_e32 v157, v159, v159
	v_fmac_f32_e32 v157, v158, v158
	v_add_f32_e32 v156, v157, v156
	v_mul_f32_e32 v157, v161, v161
	v_fmac_f32_e32 v157, v160, v160
	v_add_f32_e32 v184, v157, v156
	v_cvt_pk_bf16_f32 v157, v154, v155
	v_lshl_add_u64 v[154:155], s[78:79], 0, v[164:165]
	v_cvt_pk_bf16_f32 v156, v168, v169
	v_cvt_pk_bf16_f32 v158, v158, v159
	v_cvt_pk_bf16_f32 v159, v160, v161
	v_lshl_add_u64 v[154:155], v[212:213], 1, v[154:155]
	s_waitcnt lgkmcnt(0)
	global_store_dwordx4 v[228:229], v[222:225], off offset:256
	v_lshl_add_u64 v[226:227], v[154:155], 0, v[230:231]
	ds_bpermute_b32 v218, v243, v156
	ds_bpermute_b32 v219, v243, v157
	ds_bpermute_b32 v220, v243, v158
	ds_bpermute_b32 v221, v243, v159
	v_pk_mul_f32 v[160:161], v[80:81], v[0:1] op_sel_hi:[1,0]
	v_pk_mul_f32 v[164:165], v[78:79], v[0:1] op_sel_hi:[1,0]
	v_pk_mul_f32 v[158:159], v[86:87], v[0:1] op_sel_hi:[1,0]
	v_pk_mul_f32 v[156:157], v[88:89], v[0:1] op_sel_hi:[1,0]
	v_mul_f32_e32 v0, 0xbfb8aa3b, v158
	v_exp_f32_e32 v0, v0
	s_waitcnt vmcnt(4)
; __device__ __forceinline__ float bf_lo(unsigned w) { return __uint_as_float(w << 16); }
; __device__ __forceinline__ float bf_hi(unsigned w) { return __uint_as_float(w & 0xffff0000u); }
; __device__ __forceinline__ float sigm(float v) { return __builtin_amdgcn_rcpf(1.0f + __builtin_amdgcn_exp2f(-1.44269504089f * v)); }
; __device__ __forceinline__ u32x4 pack8(const f32x4& v0, const f32x4& v1) { u32x4 w; w.x = cvt_pk_bf16(v0[0], v0[1]); w.y = cvt_pk_bf16(v0[2], v0[3]); w.z = cvt_pk_bf16(v1[0], v1[1]); w.w = cvt_pk_bf16(v1[2], v1[3]); return w; }
; __device__ __forceinline__ float sumsq8(const f32x4& v0, const f32x4& v1) { return (v0[0] * v0[0] + v0[1] * v0[1]) + (v0[2] * v0[2] + v0[3] * v0[3]) + (v1[0] * v1[0] + v1[1] * v1[1]) + (v1[2] * v1[2] + v1[3] * v1[3]); }
; __device__ __forceinline__ void epi_run(const Epi& E, f32x4 (&acc)[2][2][4][2], const Unit& u, int wr, int wc, int fr, int fq) {
;     ...
;                 for (int mm = 0; mm < 2; ++mm) { const int m = 2 * mh + mm, row = row0 + ai * 128 + m * 16; float sq = 0.f;
; #pragma unroll
;                     for (int bj = 0; bj < 2; ++bj) { const u32x4 xx = x[mm][bj], cc = c[mm][bj];
;                         const f32x4 c0 = (f32x4){bf_lo(cc.x), bf_hi(cc.x), bf_lo(cc.y), bf_hi(cc.y)}, c1 = (f32x4){bf_lo(cc.z), bf_hi(cc.z), bf_lo(cc.w), bf_hi(cc.w)};
;                         f32x4 v0 = acc[ai][bj][m][0] * rs[ai][m], v1 = acc[ai][bj][m][1] * rs[ai][m];
; #pragma unroll
;                         for (int e = 0; e < 4; ++e) { v0[e] = sigm(v0[e]) * c0[e]; v1[e] = sigm(v1[e]) * c1[e]; }
;                         const f32x4 x0 = (f32x4){bf_lo(xx.x), bf_hi(xx.x), bf_lo(xx.y), bf_hi(xx.y)} + v0, x1 = (f32x4){bf_lo(xx.z), bf_hi(xx.z), bf_lo(xx.w), bf_hi(xx.w)} + v1;
;                         sq += sumsq8(x0, x1); *(u32x4*)(E.xout16 + (size_t)row * D + col0 + bj * 128) = pack8(x0, x1); }
;                     sq += __shfl_xor(sq, 16); sq += __shfl_xor(sq, 32); if (fq == 0) sslot[row] = sq; }
	v_lshlrev_b32_e32 v166, 16, v150
	v_and_b32_e32 v167, 0xffff0000, v150
	v_lshlrev_b32_e32 v182, 16, v151
	v_add_f32_e32 v0, 1.0, v0
	v_rcp_f32_e32 v158, v0
	v_mul_f32_e32 v0, 0xbfb8aa3b, v164
	v_exp_f32_e32 v0, v0
	v_and_b32_e32 v183, 0xffff0000, v151
	v_lshlrev_b32_e32 v168, 16, v152
	v_and_b32_e32 v169, 0xffff0000, v152
	v_add_f32_e32 v0, 1.0, v0
	v_rcp_f32_e32 v164, v0
	v_mul_f32_e32 v0, 0xbfb8aa3b, v159
	v_exp_f32_e32 v0, v0
	v_lshlrev_b32_e32 v152, 16, v153
	v_and_b32_e32 v153, 0xffff0000, v153
	v_add_f32_e32 v0, 1.0, v0
	v_rcp_f32_e32 v159, v0
	v_mul_f32_e32 v0, 0xbfb8aa3b, v165
	v_exp_f32_e32 v0, v0
	s_nop 0
	v_add_f32_e32 v0, 1.0, v0
	v_rcp_f32_e32 v165, v0
	v_mul_f32_e32 v0, 0xbfb8aa3b, v156
	v_exp_f32_e32 v0, v0
	s_nop 0
	v_add_f32_e32 v0, 1.0, v0
	v_rcp_f32_e32 v156, v0
	v_mul_f32_e32 v0, 0xbfb8aa3b, v160
	v_exp_f32_e32 v0, v0
	v_lshlrev_b32_e32 v160, 16, v146
	v_add_f32_e32 v0, 1.0, v0
	v_rcp_f32_e32 v150, v0
	v_mul_f32_e32 v0, 0xbfb8aa3b, v157
	v_exp_f32_e32 v0, v0
	s_nop 0
	v_add_f32_e32 v0, 1.0, v0
	v_rcp_f32_e32 v157, v0
	v_mul_f32_e32 v0, 0xbfb8aa3b, v161
	v_exp_f32_e32 v0, v0
	v_and_b32_e32 v161, 0xffff0000, v146
	v_lshlrev_b32_e32 v146, 16, v147
	v_and_b32_e32 v147, 0xffff0000, v147
	v_add_f32_e32 v0, 1.0, v0
	v_rcp_f32_e32 v151, v0
	v_pk_fma_f32 v[156:157], v[156:157], v[182:183], v[146:147]
	v_pk_fma_f32 v[146:147], v[158:159], v[166:167], v[160:161]
	v_lshlrev_b32_e32 v158, 16, v148
	v_and_b32_e32 v159, 0xffff0000, v148
	v_lshlrev_b32_e32 v148, 16, v149
	v_and_b32_e32 v149, 0xffff0000, v149
	v_pk_fma_f32 v[150:151], v[150:151], v[152:153], v[148:149]
	v_mul_f32_e32 v0, v147, v147
	v_mul_f32_e32 v152, v157, v157
	v_pk_fma_f32 v[148:149], v[164:165], v[168:169], v[158:159]
	v_fmac_f32_e32 v0, v146, v146
	v_fmac_f32_e32 v152, v156, v156
	v_add_f32_e32 v0, v0, v152
	v_mul_f32_e32 v152, v149, v149
	v_fmac_f32_e32 v152, v148, v148
	v_add_f32_e32 v0, v152, v0
	v_mul_f32_e32 v152, v151, v151
	v_fmac_f32_e32 v152, v150, v150
	v_add_f32_e32 v0, v152, v0
	v_add_f32_e32 v0, v184, v0
	v_cvt_pk_bf16_f32 v146, v146, v147
	v_cvt_pk_bf16_f32 v147, v156, v157
	v_cvt_pk_bf16_f32 v148, v148, v149
	v_cvt_pk_bf16_f32 v149, v150, v151
	s_waitcnt lgkmcnt(0)
	global_store_dwordx4 v[226:227], v[218:221], off
	v_lshl_add_u64 v[228:229], v[154:155], 0, v[230:231]
	ds_bpermute_b32 v222, v243, v146
	ds_bpermute_b32 v223, v243, v147
	ds_bpermute_b32 v224, v243, v148
	ds_bpermute_b32 v225, v243, v149
	ds_bpermute_b32 v146, v171, v0
	s_waitcnt lgkmcnt(0)
	v_add_f32_e32 v0, v0, v146
	ds_bpermute_b32 v146, v170, v0
	s_and_saveexec_b64 s[8:9], s[40:41]
	s_cbranch_execz .LBB0_315
	v_lshl_add_u64 v[148:149], v[210:211], 2, s[44:45]
	s_waitcnt lgkmcnt(0)
	v_add_f32_e32 v0, v0, v146
	global_store_dword v[148:149], v0, off offset:128
.LBB0_315:
	s_or_b64 exec, exec, s[8:9]
	v_add_f32_e32 v0, v180, v181
	v_fmamk_f32 v0, v0, 0x3a800000, v197
	v_rsq_f32_e32 v0, v0
	s_waitcnt vmcnt(3)
	v_lshlrev_b32_e32 v156, 16, v142
	v_and_b32_e32 v157, 0xffff0000, v142
	v_lshlrev_b32_e32 v158, 16, v144
	v_pk_mul_f32 v[154:155], v[74:75], v[0:1] op_sel_hi:[1,0]
	v_pk_mul_f32 v[148:149], v[84:85], v[0:1] op_sel_hi:[1,0]
	v_mul_f32_e32 v155, 0xbfb8aa3b, v155
	v_exp_f32_e32 v155, v155
	v_mul_f32_e32 v148, 0xbfb8aa3b, v148
	v_exp_f32_e32 v148, v148
	v_pk_mul_f32 v[152:153], v[76:77], v[0:1] op_sel_hi:[1,0]
	v_add_f32_e32 v142, 1.0, v155
	v_rcp_f32_e32 v155, v142
	v_and_b32_e32 v159, 0xffff0000, v144
	v_add_f32_e32 v142, 1.0, v148
	v_mul_f32_e32 v144, 0xbfb8aa3b, v152
	v_mul_f32_e32 v148, 0xbfb8aa3b, v149
	v_exp_f32_e32 v144, v144
	v_exp_f32_e32 v149, v148
	v_pk_mul_f32 v[150:151], v[82:83], v[0:1] op_sel_hi:[1,0]
	v_rcp_f32_e32 v148, v142
	v_mul_f32_e32 v150, 0xbfb8aa3b, v150
	v_mul_f32_e32 v151, 0xbfb8aa3b, v151
	v_exp_f32_e32 v150, v150
	v_exp_f32_e32 v151, v151
	v_add_f32_e32 v142, 1.0, v144
	v_add_f32_e32 v144, 1.0, v149
	v_mul_f32_e32 v149, 0xbfb8aa3b, v153
	v_mul_f32_e32 v154, 0xbfb8aa3b, v154
	v_exp_f32_e32 v160, v149
	v_exp_f32_e32 v154, v154
	v_add_f32_e32 v150, 1.0, v150
	v_add_f32_e32 v151, 1.0, v151
	v_rcp_f32_e32 v150, v150
	v_rcp_f32_e32 v151, v151
	v_rcp_f32_e32 v149, v144
	v_lshlrev_b32_e32 v152, 16, v143
	v_and_b32_e32 v153, 0xffff0000, v143
	v_add_f32_e32 v143, 1.0, v160
	v_add_f32_e32 v154, 1.0, v154
	v_rcp_f32_e32 v142, v142
	v_rcp_f32_e32 v143, v143
	v_rcp_f32_e32 v154, v154
	v_lshlrev_b32_e32 v160, 16, v138
	v_and_b32_e32 v161, 0xffff0000, v138
	v_lshlrev_b32_e32 v138, 16, v139
	v_and_b32_e32 v139, 0xffff0000, v139
	v_lshlrev_b32_e32 v144, 16, v145
	v_and_b32_e32 v145, 0xffff0000, v145
	v_pk_fma_f32 v[148:149], v[148:149], v[152:153], v[138:139]
	v_pk_fma_f32 v[138:139], v[150:151], v[156:157], v[160:161]
	v_lshlrev_b32_e32 v150, 16, v140
	v_and_b32_e32 v151, 0xffff0000, v140
	v_lshlrev_b32_e32 v140, 16, v141
	v_and_b32_e32 v141, 0xffff0000, v141
	v_pk_fma_f32 v[142:143], v[142:143], v[144:145], v[140:141]
	v_mul_f32_e32 v144, v139, v139
	v_mul_f32_e32 v145, v149, v149
	v_pk_fma_f32 v[140:141], v[154:155], v[158:159], v[150:151]
	v_fmac_f32_e32 v144, v138, v138
	v_fmac_f32_e32 v145, v148, v148
	v_add_f32_e32 v144, v144, v145
	v_mul_f32_e32 v145, v141, v141
	v_fmac_f32_e32 v145, v140, v140
	v_add_f32_e32 v144, v145, v144
	v_mul_f32_e32 v145, v143, v143
	v_fmac_f32_e32 v145, v142, v142
	v_cvt_pk_bf16_f32 v140, v140, v141
	v_cvt_pk_bf16_f32 v141, v142, v143
	v_pk_mul_f32 v[142:143], v[70:71], v[0:1] op_sel_hi:[1,0]
	v_pk_mul_f32 v[150:151], v[66:67], v[0:1] op_sel_hi:[1,0]
	v_mul_f32_e32 v142, 0xbfb8aa3b, v142
	v_exp_f32_e32 v142, v142
	v_add_f32_e32 v158, v145, v144
	v_cvt_pk_bf16_f32 v138, v138, v139
	v_cvt_pk_bf16_f32 v139, v148, v149
	v_pk_mul_f32 v[144:145], v[72:73], v[0:1] op_sel_hi:[1,0]
	v_pk_mul_f32 v[148:149], v[68:69], v[0:1] op_sel_hi:[1,0]
	v_add_f32_e32 v0, 1.0, v142
	v_mul_f32_e32 v142, 0xbfb8aa3b, v150
	v_exp_f32_e32 v150, v142
	v_mul_f32_e32 v142, 0xbfb8aa3b, v143
	v_exp_f32_e32 v143, v142
	v_rcp_f32_e32 v142, v0
	v_add_f32_e32 v0, 1.0, v150
	v_rcp_f32_e32 v150, v0
	v_add_f32_e32 v0, 1.0, v143
	v_mul_f32_e32 v143, 0xbfb8aa3b, v151
	v_exp_f32_e32 v151, v143
	s_waitcnt vmcnt(1)
; __device__ __forceinline__ float bf_lo(unsigned w) { return __uint_as_float(w << 16); }
; __device__ __forceinline__ float bf_hi(unsigned w) { return __uint_as_float(w & 0xffff0000u); }
; __device__ __forceinline__ float sigm(float v) { return __builtin_amdgcn_rcpf(1.0f + __builtin_amdgcn_exp2f(-1.44269504089f * v)); }
; __device__ __forceinline__ u32x4 pack8(const f32x4& v0, const f32x4& v1) { u32x4 w; w.x = cvt_pk_bf16(v0[0], v0[1]); w.y = cvt_pk_bf16(v0[2], v0[3]); w.z = cvt_pk_bf16(v1[0], v1[1]); w.w = cvt_pk_bf16(v1[2], v1[3]); return w; }
; __device__ __forceinline__ float sumsq8(const f32x4& v0, const f32x4& v1) { return (v0[0] * v0[0] + v0[1] * v0[1]) + (v0[2] * v0[2] + v0[3] * v0[3]) + (v1[0] * v1[0] + v1[1] * v1[1]) + (v1[2] * v1[2] + v1[3] * v1[3]); }
; __device__ __forceinline__ void epi_run(const Epi& E, f32x4 (&acc)[2][2][4][2], const Unit& u, int wr, int wc, int fr, int fq) {
;     ...
;                 for (int mm = 0; mm < 2; ++mm) { const int m = 2 * mh + mm, row = row0 + ai * 128 + m * 16; float sq = 0.f;
; #pragma unroll
;                     for (int bj = 0; bj < 2; ++bj) { const u32x4 xx = x[mm][bj], cc = c[mm][bj];
;                         const f32x4 c0 = (f32x4){bf_lo(cc.x), bf_hi(cc.x), bf_lo(cc.y), bf_hi(cc.y)}, c1 = (f32x4){bf_lo(cc.z), bf_hi(cc.z), bf_lo(cc.w), bf_hi(cc.w)};
;                         f32x4 v0 = acc[ai][bj][m][0] * rs[ai][m], v1 = acc[ai][bj][m][1] * rs[ai][m];
; #pragma unroll
;                         for (int e = 0; e < 4; ++e) { v0[e] = sigm(v0[e]) * c0[e]; v1[e] = sigm(v1[e]) * c1[e]; }
;                         const f32x4 x0 = (f32x4){bf_lo(xx.x), bf_hi(xx.x), bf_lo(xx.y), bf_hi(xx.y)} + v0, x1 = (f32x4){bf_lo(xx.z), bf_hi(xx.z), bf_lo(xx.w), bf_hi(xx.w)} + v1;
;                         sq += sumsq8(x0, x1); *(u32x4*)(E.xout16 + (size_t)row * D + col0 + bj * 128) = pack8(x0, x1); }
;                     sq += __shfl_xor(sq, 16); sq += __shfl_xor(sq, 32); if (fq == 0) sslot[row] = sq; }
	v_lshlrev_b32_e32 v152, 16, v134
	v_and_b32_e32 v153, 0xffff0000, v134
	v_mul_f32_e32 v134, 0xbfb8aa3b, v144
	v_exp_f32_e32 v134, v134
	v_rcp_f32_e32 v143, v0
	v_add_f32_e32 v0, 1.0, v151
	v_rcp_f32_e32 v151, v0
	v_add_f32_e32 v0, 1.0, v134
	v_mul_f32_e32 v134, 0xbfb8aa3b, v148
	v_lshlrev_b32_e32 v154, 16, v136
	v_and_b32_e32 v155, 0xffff0000, v136
	v_exp_f32_e32 v134, v134
	v_mul_f32_e32 v136, 0xbfb8aa3b, v145
	v_exp_f32_e32 v136, v136
	v_rcp_f32_e32 v144, v0
	v_add_f32_e32 v0, 1.0, v134
	v_rcp_f32_e32 v134, v0
	v_add_f32_e32 v0, 1.0, v136
	v_mul_f32_e32 v136, 0xbfb8aa3b, v149
	v_exp_f32_e32 v136, v136
	v_rcp_f32_e32 v145, v0
	v_lshlrev_b32_e32 v148, 16, v135
	v_and_b32_e32 v149, 0xffff0000, v135
	v_add_f32_e32 v0, 1.0, v136
	v_rcp_f32_e32 v135, v0
	v_lshlrev_b32_e32 v156, 16, v130
	v_and_b32_e32 v157, 0xffff0000, v130
	v_lshlrev_b32_e32 v130, 16, v131
	v_and_b32_e32 v131, 0xffff0000, v131
	v_lshlrev_b32_e32 v136, 16, v137
	v_and_b32_e32 v137, 0xffff0000, v137
	v_pk_fma_f32 v[144:145], v[144:145], v[148:149], v[130:131]
	v_pk_fma_f32 v[130:131], v[142:143], v[152:153], v[156:157]
	v_lshlrev_b32_e32 v142, 16, v132
	v_and_b32_e32 v143, 0xffff0000, v132
	v_lshlrev_b32_e32 v132, 16, v133
	v_and_b32_e32 v133, 0xffff0000, v133
	v_pk_fma_f32 v[136:137], v[134:135], v[136:137], v[132:133]
	v_mul_f32_e32 v0, v131, v131
	v_mul_f32_e32 v132, v145, v145
	v_pk_fma_f32 v[134:135], v[150:151], v[154:155], v[142:143]
	v_fmac_f32_e32 v0, v130, v130
	v_fmac_f32_e32 v132, v144, v144
	v_add_f32_e32 v0, v0, v132
	v_mul_f32_e32 v132, v135, v135
	v_fmac_f32_e32 v132, v134, v134
	v_add_f32_e32 v0, v132, v0
	v_mul_f32_e32 v132, v137, v137
	v_fmac_f32_e32 v132, v136, v136
	v_add_f32_e32 v0, v132, v0
	v_add_f32_e32 v0, v158, v0
	ds_bpermute_b32 v148, v171, v0
	s_waitcnt lgkmcnt(1)
	v_lshlrev_b64 v[146:147], 11, v[162:163]
	v_lshl_add_u64 v[132:133], s[78:79], 0, v[146:147]
	v_lshl_add_u64 v[142:143], v[212:213], 1, v[132:133]
	v_cvt_pk_bf16_f32 v132, v130, v131
	s_waitcnt lgkmcnt(0)
	v_add_f32_e32 v0, v0, v148
	ds_bpermute_b32 v130, v170, v0
	v_cvt_pk_bf16_f32 v133, v144, v145
	v_cvt_pk_bf16_f32 v134, v134, v135
	v_cvt_pk_bf16_f32 v135, v136, v137
	s_waitcnt lgkmcnt(0)
	global_store_dwordx4 v[228:229], v[222:225], off offset:256
	v_lshl_add_u64 v[226:227], v[142:143], 0, v[230:231]
	ds_bpermute_b32 v218, v243, v138
	ds_bpermute_b32 v219, v243, v139
	ds_bpermute_b32 v220, v243, v140
	ds_bpermute_b32 v221, v243, v141
	s_waitcnt lgkmcnt(0)
	global_store_dwordx4 v[226:227], v[218:221], off
	v_lshl_add_u64 v[228:229], v[142:143], 0, v[230:231]
	ds_bpermute_b32 v222, v243, v132
	ds_bpermute_b32 v223, v243, v133
	ds_bpermute_b32 v224, v243, v134
	ds_bpermute_b32 v225, v243, v135
	s_and_saveexec_b64 s[8:9], s[40:41]
	s_cbranch_execz .LBB0_317
	v_lshl_add_u64 v[132:133], v[210:211], 2, s[44:45]
	s_waitcnt lgkmcnt(0)
	v_add_f32_e32 v0, v0, v130
	global_store_dword v[132:133], v0, off offset:192
.LBB0_317:
	s_or_b64 exec, exec, s[8:9]
	v_add_u32_e32 v164, 0x80, v210
	v_ashrrev_i32_e32 v165, 31, v164
	s_waitcnt lgkmcnt(0)
	v_lshlrev_b64 v[130:131], 10, v[164:165]
	v_lshl_add_u64 v[130:131], v[130:131], 0, v[212:213]
	v_lshlrev_b64 v[130:131], 1, v[130:131]
	v_lshl_add_u64 v[132:133], s[48:49], 0, v[130:131]
	v_lshl_add_u64 v[134:135], s[62:63], 0, v[130:131]
	global_load_dwordx4 v[154:157], v[132:133], off
	global_load_dwordx4 v[158:161], v[134:135], off
	global_load_dwordx4 v[146:149], v[132:133], off offset:256
	v_or_b32_e32 v130, 0x100, v130
	v_lshl_add_u64 v[130:131], s[62:63], 0, v[130:131]
	global_load_dwordx4 v[150:153], v[130:131], off
	v_add_f32_e32 v0, v178, v179
	v_fmamk_f32 v0, v0, 0x3a800000, v197
	v_rsq_f32_e32 v0, v0
	v_add_u32_e32 v162, 0x90, v210
	v_ashrrev_i32_e32 v163, 31, v162
	v_lshlrev_b64 v[130:131], 10, v[162:163]
	v_pk_mul_f32 v[166:167], v[62:63], v[0:1] op_sel_hi:[1,0]
	v_pk_mul_f32 v[182:183], v[58:59], v[0:1] op_sel_hi:[1,0]
	v_mul_f32_e32 v167, 0xbfb8aa3b, v167
	v_exp_f32_e32 v167, v167
	v_pk_mul_f32 v[178:179], v[64:65], v[0:1] op_sel_hi:[1,0]
	v_mul_f32_e32 v166, 0xbfb8aa3b, v166
	v_exp_f32_e32 v166, v166
	v_add_f32_e32 v167, 1.0, v167
	v_rcp_f32_e32 v169, v167
	v_pk_mul_f32 v[180:181], v[60:61], v[0:1] op_sel_hi:[1,0]
	v_add_f32_e32 v166, 1.0, v166
	v_rcp_f32_e32 v168, v166
	v_mul_f32_e32 v166, 0xbfb8aa3b, v182
	v_exp_f32_e32 v166, v166
	v_lshl_add_u64 v[130:131], v[130:131], 0, v[212:213]
	v_lshlrev_b64 v[134:135], 1, v[130:131]
	v_lshl_add_u64 v[130:131], s[48:49], 0, v[134:135]
	v_add_f32_e32 v166, 1.0, v166
	v_rcp_f32_e32 v166, v166
	v_lshl_add_u64 v[132:133], s[62:63], 0, v[134:135]
	v_or_b32_e32 v134, 0x100, v134
	v_lshl_add_u64 v[134:135], s[62:63], 0, v[134:135]
	global_load_dwordx4 v[138:141], v[130:131], off
	global_load_dwordx4 v[142:145], v[132:133], off
	s_nop 0
	global_load_dwordx4 v[130:133], v[130:131], off offset:256
	v_lshlrev_b64 v[164:165], 11, v[164:165]
	global_load_dwordx4 v[134:137], v[134:135], off
	s_waitcnt vmcnt(6)
; __device__ __forceinline__ float bf_lo(unsigned w) { return __uint_as_float(w << 16); }
; __device__ __forceinline__ float bf_hi(unsigned w) { return __uint_as_float(w & 0xffff0000u); }
; __device__ __forceinline__ float sigm(float v) { return __builtin_amdgcn_rcpf(1.0f + __builtin_amdgcn_exp2f(-1.44269504089f * v)); }
; __device__ __forceinline__ u32x4 pack8(const f32x4& v0, const f32x4& v1) { u32x4 w; w.x = cvt_pk_bf16(v0[0], v0[1]); w.y = cvt_pk_bf16(v0[2], v0[3]); w.z = cvt_pk_bf16(v1[0], v1[1]); w.w = cvt_pk_bf16(v1[2], v1[3]); return w; }
; __device__ __forceinline__ float sumsq8(const f32x4& v0, const f32x4& v1) { return (v0[0] * v0[0] + v0[1] * v0[1]) + (v0[2] * v0[2] + v0[3] * v0[3]) + (v1[0] * v1[0] + v1[1] * v1[1]) + (v1[2] * v1[2] + v1[3] * v1[3]); }
; __device__ __forceinline__ void epi_run(const Epi& E, f32x4 (&acc)[2][2][4][2], const Unit& u, int wr, int wc, int fr, int fq) {
;     ...
;             for (int mh = 0; mh < 2; ++mh) { u32x4 x[2][2], c[2][2];
; #pragma unroll
;                 for (int mm = 0; mm < 2; ++mm)
; #pragma unroll
;                     for (int bj = 0; bj < 2; ++bj) { const size_t off = (size_t)(row0 + ai * 128 + (2 * mh + mm) * 16) * D + col0 + bj * 128; x[mm][bj] = *(const u32x4*)(E.xin16 + off); c[mm][bj] = *(const u32x4*)(E.C16 + off); }
; #pragma unroll
;                 for (int mm = 0; mm < 2; ++mm) { const int m = 2 * mh + mm, row = row0 + ai * 128 + m * 16; float sq = 0.f;
; #pragma unroll
;                     for (int bj = 0; bj < 2; ++bj) { const u32x4 xx = x[mm][bj], cc = c[mm][bj];
;                         const f32x4 c0 = (f32x4){bf_lo(cc.x), bf_hi(cc.x), bf_lo(cc.y), bf_hi(cc.y)}, c1 = (f32x4){bf_lo(cc.z), bf_hi(cc.z), bf_lo(cc.w), bf_hi(cc.w)};
;                         f32x4 v0 = acc[ai][bj][m][0] * rs[ai][m], v1 = acc[ai][bj][m][1] * rs[ai][m];
; #pragma unroll
;                         for (int e = 0; e < 4; ++e) { v0[e] = sigm(v0[e]) * c0[e]; v1[e] = sigm(v1[e]) * c1[e]; }
;                         const f32x4 x0 = (f32x4){bf_lo(xx.x), bf_hi(xx.x), bf_lo(xx.y), bf_hi(xx.y)} + v0, x1 = (f32x4){bf_lo(xx.z), bf_hi(xx.z), bf_lo(xx.w), bf_hi(xx.w)} + v1;
;                         sq += sumsq8(x0, x1); *(u32x4*)(E.xout16 + (size_t)row * D + col0 + bj * 128) = pack8(x0, x1); }
;                     sq += __shfl_xor(sq, 16); sq += __shfl_xor(sq, 32); if (fq == 0) sslot[row] = sq; }
	v_lshlrev_b32_e32 v184, 16, v158
	v_and_b32_e32 v185, 0xffff0000, v158
	v_mul_f32_e32 v158, 0xbfb8aa3b, v183
	v_exp_f32_e32 v158, v158
	v_lshlrev_b32_e32 v182, 16, v160
	v_and_b32_e32 v183, 0xffff0000, v160
	v_mul_f32_e32 v160, 0xbfb8aa3b, v179
	v_add_f32_e32 v158, 1.0, v158
	v_rcp_f32_e32 v167, v158
	v_mul_f32_e32 v158, 0xbfb8aa3b, v178
	v_exp_f32_e32 v158, v158
	v_exp_f32_e32 v160, v160
	v_lshlrev_b32_e32 v186, 16, v159
	v_and_b32_e32 v187, 0xffff0000, v159
	v_add_f32_e32 v158, 1.0, v158
	v_rcp_f32_e32 v178, v158
	v_mul_f32_e32 v158, 0xbfb8aa3b, v180
	v_mul_f32_e32 v159, 0xbfb8aa3b, v181
	v_exp_f32_e32 v158, v158
	v_exp_f32_e32 v159, v159
	v_add_f32_e32 v160, 1.0, v160
	v_rcp_f32_e32 v179, v160
	v_add_f32_e32 v158, 1.0, v158
	v_add_f32_e32 v159, 1.0, v159
	v_rcp_f32_e32 v158, v158
	v_rcp_f32_e32 v159, v159
	v_lshlrev_b32_e32 v180, 16, v154
	v_and_b32_e32 v181, 0xffff0000, v154
	v_lshlrev_b32_e32 v154, 16, v155
	v_and_b32_e32 v155, 0xffff0000, v155
	v_lshlrev_b32_e32 v160, 16, v161
	v_and_b32_e32 v161, 0xffff0000, v161
	v_pk_fma_f32 v[154:155], v[178:179], v[186:187], v[154:155]
	v_pk_fma_f32 v[168:169], v[168:169], v[184:185], v[180:181]
	v_lshlrev_b32_e32 v178, 16, v156
	v_and_b32_e32 v179, 0xffff0000, v156
	v_lshlrev_b32_e32 v156, 16, v157
	v_and_b32_e32 v157, 0xffff0000, v157
	v_pk_fma_f32 v[160:161], v[158:159], v[160:161], v[156:157]
	v_mul_f32_e32 v156, v169, v169
	v_mul_f32_e32 v157, v155, v155
	v_pk_fma_f32 v[158:159], v[166:167], v[182:183], v[178:179]
	v_fmac_f32_e32 v156, v168, v168
	v_fmac_f32_e32 v157, v154, v154
	v_add_f32_e32 v156, v156, v157
	v_mul_f32_e32 v157, v159, v159
	v_fmac_f32_e32 v157, v158, v158
	v_add_f32_e32 v156, v157, v156
	v_mul_f32_e32 v157, v161, v161
	v_fmac_f32_e32 v157, v160, v160
	v_add_f32_e32 v180, v157, v156
	v_cvt_pk_bf16_f32 v157, v154, v155
	v_lshl_add_u64 v[154:155], s[78:79], 0, v[164:165]
	v_cvt_pk_bf16_f32 v156, v168, v169
	v_cvt_pk_bf16_f32 v158, v158, v159
	v_cvt_pk_bf16_f32 v159, v160, v161
	v_lshl_add_u64 v[154:155], v[212:213], 1, v[154:155]
	s_waitcnt lgkmcnt(0)
	global_store_dwordx4 v[228:229], v[222:225], off offset:256
	v_lshl_add_u64 v[226:227], v[154:155], 0, v[230:231]
	ds_bpermute_b32 v218, v243, v156
	ds_bpermute_b32 v219, v243, v157
	ds_bpermute_b32 v220, v243, v158
	ds_bpermute_b32 v221, v243, v159
	v_pk_mul_f32 v[160:161], v[52:53], v[0:1] op_sel_hi:[1,0]
	v_pk_mul_f32 v[164:165], v[50:51], v[0:1] op_sel_hi:[1,0]
	v_pk_mul_f32 v[158:159], v[54:55], v[0:1] op_sel_hi:[1,0]
	v_pk_mul_f32 v[156:157], v[56:57], v[0:1] op_sel_hi:[1,0]
	v_mul_f32_e32 v0, 0xbfb8aa3b, v158
	v_exp_f32_e32 v0, v0
	s_waitcnt vmcnt(4)
	v_lshlrev_b32_e32 v166, 16, v150
	v_and_b32_e32 v167, 0xffff0000, v150
	v_lshlrev_b32_e32 v178, 16, v151
	v_add_f32_e32 v0, 1.0, v0
	v_rcp_f32_e32 v158, v0
	v_mul_f32_e32 v0, 0xbfb8aa3b, v164
	v_exp_f32_e32 v0, v0
	v_and_b32_e32 v179, 0xffff0000, v151
	v_lshlrev_b32_e32 v168, 16, v152
	v_and_b32_e32 v169, 0xffff0000, v152
	v_add_f32_e32 v0, 1.0, v0
	v_rcp_f32_e32 v164, v0
	v_mul_f32_e32 v0, 0xbfb8aa3b, v159
	v_exp_f32_e32 v0, v0
	v_lshlrev_b32_e32 v152, 16, v153
	v_and_b32_e32 v153, 0xffff0000, v153
	v_add_f32_e32 v0, 1.0, v0
	v_rcp_f32_e32 v159, v0
	v_mul_f32_e32 v0, 0xbfb8aa3b, v165
	v_exp_f32_e32 v0, v0
	s_nop 0
	v_add_f32_e32 v0, 1.0, v0
	v_rcp_f32_e32 v165, v0
	v_mul_f32_e32 v0, 0xbfb8aa3b, v156
	v_exp_f32_e32 v0, v0
	s_nop 0
	v_add_f32_e32 v0, 1.0, v0
	v_rcp_f32_e32 v156, v0
	v_mul_f32_e32 v0, 0xbfb8aa3b, v160
	v_exp_f32_e32 v0, v0
	v_lshlrev_b32_e32 v160, 16, v146
	v_add_f32_e32 v0, 1.0, v0
	v_rcp_f32_e32 v150, v0
	v_mul_f32_e32 v0, 0xbfb8aa3b, v157
	v_exp_f32_e32 v0, v0
	s_nop 0
	v_add_f32_e32 v0, 1.0, v0
	v_rcp_f32_e32 v157, v0
	v_mul_f32_e32 v0, 0xbfb8aa3b, v161
	v_exp_f32_e32 v0, v0
	v_and_b32_e32 v161, 0xffff0000, v146
	v_lshlrev_b32_e32 v146, 16, v147
	v_and_b32_e32 v147, 0xffff0000, v147
	v_add_f32_e32 v0, 1.0, v0
	v_rcp_f32_e32 v151, v0
	v_pk_fma_f32 v[156:157], v[156:157], v[178:179], v[146:147]
	v_pk_fma_f32 v[146:147], v[158:159], v[166:167], v[160:161]
	v_lshlrev_b32_e32 v158, 16, v148
	v_and_b32_e32 v159, 0xffff0000, v148
	v_lshlrev_b32_e32 v148, 16, v149
	v_and_b32_e32 v149, 0xffff0000, v149
	v_pk_fma_f32 v[150:151], v[150:151], v[152:153], v[148:149]
	v_mul_f32_e32 v0, v147, v147
	v_mul_f32_e32 v152, v157, v157
	v_pk_fma_f32 v[148:149], v[164:165], v[168:169], v[158:159]
	v_fmac_f32_e32 v0, v146, v146
	v_fmac_f32_e32 v152, v156, v156
	v_add_f32_e32 v0, v0, v152
	v_mul_f32_e32 v152, v149, v149
	v_fmac_f32_e32 v152, v148, v148
	v_add_f32_e32 v0, v152, v0
	v_mul_f32_e32 v152, v151, v151
	v_fmac_f32_e32 v152, v150, v150
	v_add_f32_e32 v0, v152, v0
	v_add_f32_e32 v0, v180, v0
	v_cvt_pk_bf16_f32 v146, v146, v147
	v_cvt_pk_bf16_f32 v147, v156, v157
	v_cvt_pk_bf16_f32 v148, v148, v149
	v_cvt_pk_bf16_f32 v149, v150, v151
	s_waitcnt lgkmcnt(0)
	global_store_dwordx4 v[226:227], v[218:221], off
	v_lshl_add_u64 v[228:229], v[154:155], 0, v[230:231]
	ds_bpermute_b32 v222, v243, v146
	ds_bpermute_b32 v223, v243, v147
	ds_bpermute_b32 v224, v243, v148
	ds_bpermute_b32 v225, v243, v149
	ds_bpermute_b32 v146, v171, v0
	s_waitcnt lgkmcnt(0)
	v_add_f32_e32 v0, v0, v146
	ds_bpermute_b32 v146, v170, v0
	s_and_saveexec_b64 s[8:9], s[40:41]
	s_cbranch_execz .LBB0_319
	v_lshl_add_u64 v[148:149], v[210:211], 2, s[44:45]
	s_waitcnt lgkmcnt(0)
	v_add_f32_e32 v0, v0, v146
	global_store_dword v[148:149], v0, off offset:512
; __device__ __forceinline__ float bf_lo(unsigned w) { return __uint_as_float(w << 16); }
; __device__ __forceinline__ float bf_hi(unsigned w) { return __uint_as_float(w & 0xffff0000u); }
; __device__ __forceinline__ float sigm(float v) { return __builtin_amdgcn_rcpf(1.0f + __builtin_amdgcn_exp2f(-1.44269504089f * v)); }
; __device__ __forceinline__ u32x4 pack8(const f32x4& v0, const f32x4& v1) { u32x4 w; w.x = cvt_pk_bf16(v0[0], v0[1]); w.y = cvt_pk_bf16(v0[2], v0[3]); w.z = cvt_pk_bf16(v1[0], v1[1]); w.w = cvt_pk_bf16(v1[2], v1[3]); return w; }
; __device__ __forceinline__ float sumsq8(const f32x4& v0, const f32x4& v1) { return (v0[0] * v0[0] + v0[1] * v0[1]) + (v0[2] * v0[2] + v0[3] * v0[3]) + (v1[0] * v1[0] + v1[1] * v1[1]) + (v1[2] * v1[2] + v1[3] * v1[3]); }
; __device__ __forceinline__ void epi_run(const Epi& E, f32x4 (&acc)[2][2][4][2], const Unit& u, int wr, int wc, int fr, int fq) {
;     ...
;             for (int mh = 0; mh < 2; ++mh) { u32x4 x[2][2], c[2][2];
; #pragma unroll
;                 for (int mm = 0; mm < 2; ++mm)
; #pragma unroll
;                     for (int bj = 0; bj < 2; ++bj) { const size_t off = (size_t)(row0 + ai * 128 + (2 * mh + mm) * 16) * D + col0 + bj * 128; x[mm][bj] = *(const u32x4*)(E.xin16 + off); c[mm][bj] = *(const u32x4*)(E.C16 + off); }
; #pragma unroll
;                 for (int mm = 0; mm < 2; ++mm) { const int m = 2 * mh + mm, row = row0 + ai * 128 + m * 16; float sq = 0.f;
; #pragma unroll
;                     for (int bj = 0; bj < 2; ++bj) { const u32x4 xx = x[mm][bj], cc = c[mm][bj];
;                         const f32x4 c0 = (f32x4){bf_lo(cc.x), bf_hi(cc.x), bf_lo(cc.y), bf_hi(cc.y)}, c1 = (f32x4){bf_lo(cc.z), bf_hi(cc.z), bf_lo(cc.w), bf_hi(cc.w)};
;                         f32x4 v0 = acc[ai][bj][m][0] * rs[ai][m], v1 = acc[ai][bj][m][1] * rs[ai][m];
; #pragma unroll
;                         for (int e = 0; e < 4; ++e) { v0[e] = sigm(v0[e]) * c0[e]; v1[e] = sigm(v1[e]) * c1[e]; }
;                         const f32x4 x0 = (f32x4){bf_lo(xx.x), bf_hi(xx.x), bf_lo(xx.y), bf_hi(xx.y)} + v0, x1 = (f32x4){bf_lo(xx.z), bf_hi(xx.z), bf_lo(xx.w), bf_hi(xx.w)} + v1;
;                         sq += sumsq8(x0, x1); *(u32x4*)(E.xout16 + (size_t)row * D + col0 + bj * 128) = pack8(x0, x1); }
;                     sq += __shfl_xor(sq, 16); sq += __shfl_xor(sq, 32); if (fq == 0) sslot[row] = sq; }
.LBB0_319:
	s_or_b64 exec, exec, s[8:9]
	v_add_f32_e32 v0, v176, v177
	v_fmamk_f32 v0, v0, 0x3a800000, v197
	v_rsq_f32_e32 v0, v0
	s_waitcnt vmcnt(3)
	v_lshlrev_b32_e32 v156, 16, v142
	v_and_b32_e32 v157, 0xffff0000, v142
	v_lshlrev_b32_e32 v158, 16, v144
	v_pk_mul_f32 v[154:155], v[42:43], v[0:1] op_sel_hi:[1,0]
	v_pk_mul_f32 v[148:149], v[48:49], v[0:1] op_sel_hi:[1,0]
	v_mul_f32_e32 v155, 0xbfb8aa3b, v155
	v_exp_f32_e32 v155, v155
	v_mul_f32_e32 v148, 0xbfb8aa3b, v148
	v_exp_f32_e32 v148, v148
	v_pk_mul_f32 v[152:153], v[44:45], v[0:1] op_sel_hi:[1,0]
	v_add_f32_e32 v142, 1.0, v155
	v_rcp_f32_e32 v155, v142
	v_and_b32_e32 v159, 0xffff0000, v144
	v_add_f32_e32 v142, 1.0, v148
	v_mul_f32_e32 v144, 0xbfb8aa3b, v152
	v_mul_f32_e32 v148, 0xbfb8aa3b, v149
	v_exp_f32_e32 v144, v144
	v_exp_f32_e32 v149, v148
	v_pk_mul_f32 v[150:151], v[46:47], v[0:1] op_sel_hi:[1,0]
	v_rcp_f32_e32 v148, v142
	v_mul_f32_e32 v150, 0xbfb8aa3b, v150
	v_mul_f32_e32 v151, 0xbfb8aa3b, v151
	v_exp_f32_e32 v150, v150
	v_exp_f32_e32 v151, v151
	v_add_f32_e32 v142, 1.0, v144
	v_add_f32_e32 v144, 1.0, v149
	v_mul_f32_e32 v149, 0xbfb8aa3b, v153
	v_mul_f32_e32 v154, 0xbfb8aa3b, v154
	v_exp_f32_e32 v160, v149
	v_exp_f32_e32 v154, v154
	v_add_f32_e32 v150, 1.0, v150
	v_add_f32_e32 v151, 1.0, v151
	v_rcp_f32_e32 v150, v150
	v_rcp_f32_e32 v151, v151
	v_rcp_f32_e32 v149, v144
	v_lshlrev_b32_e32 v152, 16, v143
	v_and_b32_e32 v153, 0xffff0000, v143
	v_add_f32_e32 v143, 1.0, v160
	v_add_f32_e32 v154, 1.0, v154
	v_rcp_f32_e32 v142, v142
	v_rcp_f32_e32 v143, v143
	v_rcp_f32_e32 v154, v154
	v_lshlrev_b32_e32 v160, 16, v138
	v_and_b32_e32 v161, 0xffff0000, v138
	v_lshlrev_b32_e32 v138, 16, v139
	v_and_b32_e32 v139, 0xffff0000, v139
	v_lshlrev_b32_e32 v144, 16, v145
	v_and_b32_e32 v145, 0xffff0000, v145
	v_pk_fma_f32 v[148:149], v[148:149], v[152:153], v[138:139]
	v_pk_fma_f32 v[138:139], v[150:151], v[156:157], v[160:161]
	v_lshlrev_b32_e32 v150, 16, v140
	v_and_b32_e32 v151, 0xffff0000, v140
	v_lshlrev_b32_e32 v140, 16, v141
	v_and_b32_e32 v141, 0xffff0000, v141
	v_pk_fma_f32 v[142:143], v[142:143], v[144:145], v[140:141]
	v_mul_f32_e32 v144, v139, v139
	v_mul_f32_e32 v145, v149, v149
	v_pk_fma_f32 v[140:141], v[154:155], v[158:159], v[150:151]
	v_fmac_f32_e32 v144, v138, v138
	v_fmac_f32_e32 v145, v148, v148
	v_add_f32_e32 v144, v144, v145
	v_mul_f32_e32 v145, v141, v141
	v_fmac_f32_e32 v145, v140, v140
	v_add_f32_e32 v144, v145, v144
	v_mul_f32_e32 v145, v143, v143
	v_fmac_f32_e32 v145, v142, v142
	v_cvt_pk_bf16_f32 v140, v140, v141
	v_cvt_pk_bf16_f32 v141, v142, v143
	v_pk_mul_f32 v[142:143], v[38:39], v[0:1] op_sel_hi:[1,0]
	v_pk_mul_f32 v[150:151], v[34:35], v[0:1] op_sel_hi:[1,0]
	v_mul_f32_e32 v142, 0xbfb8aa3b, v142
	v_exp_f32_e32 v142, v142
	v_add_f32_e32 v158, v145, v144
	v_cvt_pk_bf16_f32 v138, v138, v139
	v_cvt_pk_bf16_f32 v139, v148, v149
	v_pk_mul_f32 v[144:145], v[40:41], v[0:1] op_sel_hi:[1,0]
	v_pk_mul_f32 v[148:149], v[36:37], v[0:1] op_sel_hi:[1,0]
	v_add_f32_e32 v0, 1.0, v142
	v_mul_f32_e32 v142, 0xbfb8aa3b, v150
	v_exp_f32_e32 v150, v142
	v_mul_f32_e32 v142, 0xbfb8aa3b, v143
	v_exp_f32_e32 v143, v142
	v_rcp_f32_e32 v142, v0
	v_add_f32_e32 v0, 1.0, v150
	v_rcp_f32_e32 v150, v0
	v_add_f32_e32 v0, 1.0, v143
	v_mul_f32_e32 v143, 0xbfb8aa3b, v151
	v_exp_f32_e32 v151, v143
	s_waitcnt vmcnt(1)
	v_lshlrev_b32_e32 v152, 16, v134
	v_and_b32_e32 v153, 0xffff0000, v134
	v_mul_f32_e32 v134, 0xbfb8aa3b, v144
	v_exp_f32_e32 v134, v134
	v_rcp_f32_e32 v143, v0
	v_add_f32_e32 v0, 1.0, v151
	v_rcp_f32_e32 v151, v0
	v_add_f32_e32 v0, 1.0, v134
	v_mul_f32_e32 v134, 0xbfb8aa3b, v148
	v_lshlrev_b32_e32 v154, 16, v136
	v_and_b32_e32 v155, 0xffff0000, v136
	v_exp_f32_e32 v134, v134
	v_mul_f32_e32 v136, 0xbfb8aa3b, v145
	v_exp_f32_e32 v136, v136
	v_rcp_f32_e32 v144, v0
	v_add_f32_e32 v0, 1.0, v134
	v_rcp_f32_e32 v134, v0
	v_add_f32_e32 v0, 1.0, v136
	v_mul_f32_e32 v136, 0xbfb8aa3b, v149
	v_exp_f32_e32 v136, v136
	v_rcp_f32_e32 v145, v0
	v_lshlrev_b32_e32 v148, 16, v135
	v_and_b32_e32 v149, 0xffff0000, v135
	v_add_f32_e32 v0, 1.0, v136
	v_rcp_f32_e32 v135, v0
	v_lshlrev_b32_e32 v156, 16, v130
	v_and_b32_e32 v157, 0xffff0000, v130
	v_lshlrev_b32_e32 v130, 16, v131
	v_and_b32_e32 v131, 0xffff0000, v131
	v_lshlrev_b32_e32 v136, 16, v137
	v_and_b32_e32 v137, 0xffff0000, v137
	v_pk_fma_f32 v[144:145], v[144:145], v[148:149], v[130:131]
	v_pk_fma_f32 v[130:131], v[142:143], v[152:153], v[156:157]
	v_lshlrev_b32_e32 v142, 16, v132
	v_and_b32_e32 v143, 0xffff0000, v132
	v_lshlrev_b32_e32 v132, 16, v133
	v_and_b32_e32 v133, 0xffff0000, v133
	v_pk_fma_f32 v[136:137], v[134:135], v[136:137], v[132:133]
	v_mul_f32_e32 v0, v131, v131
	v_mul_f32_e32 v132, v145, v145
	v_pk_fma_f32 v[134:135], v[150:151], v[154:155], v[142:143]
	v_fmac_f32_e32 v0, v130, v130
	v_fmac_f32_e32 v132, v144, v144
	v_add_f32_e32 v0, v0, v132
	v_mul_f32_e32 v132, v135, v135
	v_fmac_f32_e32 v132, v134, v134
	v_add_f32_e32 v0, v132, v0
	v_mul_f32_e32 v132, v137, v137
	v_fmac_f32_e32 v132, v136, v136
	v_add_f32_e32 v0, v132, v0
	v_add_f32_e32 v0, v158, v0
	ds_bpermute_b32 v148, v171, v0
	s_waitcnt lgkmcnt(1)
	v_lshlrev_b64 v[146:147], 11, v[162:163]
	v_lshl_add_u64 v[132:133], s[78:79], 0, v[146:147]
	v_lshl_add_u64 v[142:143], v[212:213], 1, v[132:133]
	v_cvt_pk_bf16_f32 v132, v130, v131
	s_waitcnt lgkmcnt(0)
	v_add_f32_e32 v0, v0, v148
	ds_bpermute_b32 v130, v170, v0
	v_cvt_pk_bf16_f32 v133, v144, v145
	v_cvt_pk_bf16_f32 v134, v134, v135
	v_cvt_pk_bf16_f32 v135, v136, v137
	s_waitcnt lgkmcnt(0)
	global_store_dwordx4 v[228:229], v[222:225], off offset:256
	v_lshl_add_u64 v[226:227], v[142:143], 0, v[230:231]
	ds_bpermute_b32 v218, v243, v138
	ds_bpermute_b32 v219, v243, v139
	ds_bpermute_b32 v220, v243, v140
	ds_bpermute_b32 v221, v243, v141
	s_waitcnt lgkmcnt(0)
	global_store_dwordx4 v[226:227], v[218:221], off
	v_lshl_add_u64 v[228:229], v[142:143], 0, v[230:231]
	ds_bpermute_b32 v222, v243, v132
	ds_bpermute_b32 v223, v243, v133
	ds_bpermute_b32 v224, v243, v134
	ds_bpermute_b32 v225, v243, v135
	s_and_saveexec_b64 s[8:9], s[40:41]
	s_cbranch_execz .LBB0_321
	v_lshl_add_u64 v[132:133], v[210:211], 2, s[44:45]
	s_waitcnt lgkmcnt(0)
	v_add_f32_e32 v0, v0, v130
	global_store_dword v[132:133], v0, off offset:576
; __device__ __forceinline__ float bf_lo(unsigned w) { return __uint_as_float(w << 16); }
; __device__ __forceinline__ float bf_hi(unsigned w) { return __uint_as_float(w & 0xffff0000u); }
; __device__ __forceinline__ float sigm(float v) { return __builtin_amdgcn_rcpf(1.0f + __builtin_amdgcn_exp2f(-1.44269504089f * v)); }
; __device__ __forceinline__ u32x4 pack8(const f32x4& v0, const f32x4& v1) { u32x4 w; w.x = cvt_pk_bf16(v0[0], v0[1]); w.y = cvt_pk_bf16(v0[2], v0[3]); w.z = cvt_pk_bf16(v1[0], v1[1]); w.w = cvt_pk_bf16(v1[2], v1[3]); return w; }
; __device__ __forceinline__ float sumsq8(const f32x4& v0, const f32x4& v1) { return (v0[0] * v0[0] + v0[1] * v0[1]) + (v0[2] * v0[2] + v0[3] * v0[3]) + (v1[0] * v1[0] + v1[1] * v1[1]) + (v1[2] * v1[2] + v1[3] * v1[3]); }
; __device__ __forceinline__ void epi_run(const Epi& E, f32x4 (&acc)[2][2][4][2], const Unit& u, int wr, int wc, int fr, int fq) {
;     ...
;                 for (int mm = 0; mm < 2; ++mm)
; #pragma unroll
;                     for (int bj = 0; bj < 2; ++bj) { const size_t off = (size_t)(row0 + ai * 128 + (2 * mh + mm) * 16) * D + col0 + bj * 128; x[mm][bj] = *(const u32x4*)(E.xin16 + off); c[mm][bj] = *(const u32x4*)(E.C16 + off); }
; #pragma unroll
;                 for (int mm = 0; mm < 2; ++mm) { const int m = 2 * mh + mm, row = row0 + ai * 128 + m * 16; float sq = 0.f;
; #pragma unroll
;                     for (int bj = 0; bj < 2; ++bj) { const u32x4 xx = x[mm][bj], cc = c[mm][bj];
;                         const f32x4 c0 = (f32x4){bf_lo(cc.x), bf_hi(cc.x), bf_lo(cc.y), bf_hi(cc.y)}, c1 = (f32x4){bf_lo(cc.z), bf_hi(cc.z), bf_lo(cc.w), bf_hi(cc.w)};
;                         f32x4 v0 = acc[ai][bj][m][0] * rs[ai][m], v1 = acc[ai][bj][m][1] * rs[ai][m];
; #pragma unroll
;                         for (int e = 0; e < 4; ++e) { v0[e] = sigm(v0[e]) * c0[e]; v1[e] = sigm(v1[e]) * c1[e]; }
;                         const f32x4 x0 = (f32x4){bf_lo(xx.x), bf_hi(xx.x), bf_lo(xx.y), bf_hi(xx.y)} + v0, x1 = (f32x4){bf_lo(xx.z), bf_hi(xx.z), bf_lo(xx.w), bf_hi(xx.w)} + v1;
;                         sq += sumsq8(x0, x1); *(u32x4*)(E.xout16 + (size_t)row * D + col0 + bj * 128) = pack8(x0, x1); }
;                     sq += __shfl_xor(sq, 16); sq += __shfl_xor(sq, 32); if (fq == 0) sslot[row] = sq; }
.LBB0_321:
	s_or_b64 exec, exec, s[8:9]
	v_add_u32_e32 v164, 0xa0, v210
	v_ashrrev_i32_e32 v165, 31, v164
	s_waitcnt lgkmcnt(0)
	v_lshlrev_b64 v[130:131], 10, v[164:165]
	v_lshl_add_u64 v[130:131], v[130:131], 0, v[212:213]
	v_lshlrev_b64 v[130:131], 1, v[130:131]
	v_lshl_add_u64 v[132:133], s[48:49], 0, v[130:131]
	v_lshl_add_u64 v[134:135], s[62:63], 0, v[130:131]
	global_load_dwordx4 v[154:157], v[132:133], off
	global_load_dwordx4 v[158:161], v[134:135], off
	global_load_dwordx4 v[146:149], v[132:133], off offset:256
	v_or_b32_e32 v130, 0x100, v130
	v_lshl_add_u64 v[130:131], s[62:63], 0, v[130:131]
	global_load_dwordx4 v[150:153], v[130:131], off
	v_add_f32_e32 v0, v174, v175
	v_fmamk_f32 v0, v0, 0x3a800000, v197
	v_rsq_f32_e32 v0, v0
	v_add_u32_e32 v162, 0xb0, v210
	v_ashrrev_i32_e32 v163, 31, v162
	v_lshlrev_b64 v[130:131], 10, v[162:163]
	v_pk_mul_f32 v[166:167], v[30:31], v[0:1] op_sel_hi:[1,0]
	v_pk_mul_f32 v[178:179], v[26:27], v[0:1] op_sel_hi:[1,0]
	v_mul_f32_e32 v167, 0xbfb8aa3b, v167
	v_exp_f32_e32 v167, v167
	v_pk_mul_f32 v[174:175], v[32:33], v[0:1] op_sel_hi:[1,0]
	v_mul_f32_e32 v166, 0xbfb8aa3b, v166
	v_exp_f32_e32 v166, v166
	v_add_f32_e32 v167, 1.0, v167
	v_rcp_f32_e32 v169, v167
	v_pk_mul_f32 v[176:177], v[28:29], v[0:1] op_sel_hi:[1,0]
	v_add_f32_e32 v166, 1.0, v166
	v_rcp_f32_e32 v168, v166
	v_mul_f32_e32 v166, 0xbfb8aa3b, v178
	v_exp_f32_e32 v166, v166
	v_lshl_add_u64 v[130:131], v[130:131], 0, v[212:213]
	v_lshlrev_b64 v[134:135], 1, v[130:131]
	v_lshl_add_u64 v[130:131], s[48:49], 0, v[134:135]
	v_add_f32_e32 v166, 1.0, v166
	v_rcp_f32_e32 v166, v166
	v_lshl_add_u64 v[132:133], s[62:63], 0, v[134:135]
	v_or_b32_e32 v134, 0x100, v134
	v_lshl_add_u64 v[134:135], s[62:63], 0, v[134:135]
	global_load_dwordx4 v[138:141], v[130:131], off
	global_load_dwordx4 v[142:145], v[132:133], off
	s_nop 0
	global_load_dwordx4 v[130:133], v[130:131], off offset:256
	v_lshlrev_b64 v[164:165], 11, v[164:165]
	global_load_dwordx4 v[134:137], v[134:135], off
	s_waitcnt vmcnt(6)
	v_lshlrev_b32_e32 v180, 16, v158
	v_and_b32_e32 v181, 0xffff0000, v158
	v_mul_f32_e32 v158, 0xbfb8aa3b, v179
	v_exp_f32_e32 v158, v158
	v_lshlrev_b32_e32 v178, 16, v160
	v_and_b32_e32 v179, 0xffff0000, v160
	v_mul_f32_e32 v160, 0xbfb8aa3b, v175
	v_add_f32_e32 v158, 1.0, v158
	v_rcp_f32_e32 v167, v158
	v_mul_f32_e32 v158, 0xbfb8aa3b, v174
	v_exp_f32_e32 v158, v158
	v_exp_f32_e32 v160, v160
	v_lshlrev_b32_e32 v182, 16, v159
	v_and_b32_e32 v183, 0xffff0000, v159
	v_add_f32_e32 v158, 1.0, v158
	v_rcp_f32_e32 v174, v158
	v_mul_f32_e32 v158, 0xbfb8aa3b, v176
	v_mul_f32_e32 v159, 0xbfb8aa3b, v177
	v_exp_f32_e32 v158, v158
	v_exp_f32_e32 v159, v159
	v_add_f32_e32 v160, 1.0, v160
	v_rcp_f32_e32 v175, v160
	v_add_f32_e32 v158, 1.0, v158
	v_add_f32_e32 v159, 1.0, v159
	v_rcp_f32_e32 v158, v158
	v_rcp_f32_e32 v159, v159
	v_lshlrev_b32_e32 v176, 16, v154
	v_and_b32_e32 v177, 0xffff0000, v154
	v_lshlrev_b32_e32 v154, 16, v155
	v_and_b32_e32 v155, 0xffff0000, v155
	v_lshlrev_b32_e32 v160, 16, v161
	v_and_b32_e32 v161, 0xffff0000, v161
	v_pk_fma_f32 v[154:155], v[174:175], v[182:183], v[154:155]
	v_pk_fma_f32 v[168:169], v[168:169], v[180:181], v[176:177]
	v_lshlrev_b32_e32 v174, 16, v156
	v_and_b32_e32 v175, 0xffff0000, v156
	v_lshlrev_b32_e32 v156, 16, v157
	v_and_b32_e32 v157, 0xffff0000, v157
	v_pk_fma_f32 v[160:161], v[158:159], v[160:161], v[156:157]
	v_mul_f32_e32 v156, v169, v169
	v_mul_f32_e32 v157, v155, v155
	v_pk_fma_f32 v[158:159], v[166:167], v[178:179], v[174:175]
	v_fmac_f32_e32 v156, v168, v168
	v_fmac_f32_e32 v157, v154, v154
	v_add_f32_e32 v156, v156, v157
	v_mul_f32_e32 v157, v159, v159
	v_fmac_f32_e32 v157, v158, v158
	v_add_f32_e32 v156, v157, v156
	v_mul_f32_e32 v157, v161, v161
	v_fmac_f32_e32 v157, v160, v160
	v_add_f32_e32 v176, v157, v156
	v_cvt_pk_bf16_f32 v157, v154, v155
	v_lshl_add_u64 v[154:155], s[78:79], 0, v[164:165]
	v_cvt_pk_bf16_f32 v156, v168, v169
	v_cvt_pk_bf16_f32 v158, v158, v159
	v_cvt_pk_bf16_f32 v159, v160, v161
	v_lshl_add_u64 v[154:155], v[212:213], 1, v[154:155]
	s_waitcnt lgkmcnt(0)
	global_store_dwordx4 v[228:229], v[222:225], off offset:256
	v_lshl_add_u64 v[226:227], v[154:155], 0, v[230:231]
	ds_bpermute_b32 v218, v243, v156
	ds_bpermute_b32 v219, v243, v157
	ds_bpermute_b32 v220, v243, v158
	ds_bpermute_b32 v221, v243, v159
	v_pk_mul_f32 v[160:161], v[20:21], v[0:1] op_sel_hi:[1,0]
	v_pk_mul_f32 v[164:165], v[18:19], v[0:1] op_sel_hi:[1,0]
	v_pk_mul_f32 v[158:159], v[22:23], v[0:1] op_sel_hi:[1,0]
	v_pk_mul_f32 v[156:157], v[24:25], v[0:1] op_sel_hi:[1,0]
	v_mul_f32_e32 v0, 0xbfb8aa3b, v158
	v_exp_f32_e32 v0, v0
	s_waitcnt vmcnt(4)
; __device__ __forceinline__ float bf_lo(unsigned w) { return __uint_as_float(w << 16); }
; __device__ __forceinline__ float bf_hi(unsigned w) { return __uint_as_float(w & 0xffff0000u); }
; __device__ __forceinline__ float sigm(float v) { return __builtin_amdgcn_rcpf(1.0f + __builtin_amdgcn_exp2f(-1.44269504089f * v)); }
; __device__ __forceinline__ u32x4 pack8(const f32x4& v0, const f32x4& v1) { u32x4 w; w.x = cvt_pk_bf16(v0[0], v0[1]); w.y = cvt_pk_bf16(v0[2], v0[3]); w.z = cvt_pk_bf16(v1[0], v1[1]); w.w = cvt_pk_bf16(v1[2], v1[3]); return w; }
; __device__ __forceinline__ float sumsq8(const f32x4& v0, const f32x4& v1) { return (v0[0] * v0[0] + v0[1] * v0[1]) + (v0[2] * v0[2] + v0[3] * v0[3]) + (v1[0] * v1[0] + v1[1] * v1[1]) + (v1[2] * v1[2] + v1[3] * v1[3]); }
; __device__ __forceinline__ void epi_run(const Epi& E, f32x4 (&acc)[2][2][4][2], const Unit& u, int wr, int wc, int fr, int fq) {
;     ...
;                 for (int mm = 0; mm < 2; ++mm) { const int m = 2 * mh + mm, row = row0 + ai * 128 + m * 16; float sq = 0.f;
; #pragma unroll
;                     for (int bj = 0; bj < 2; ++bj) { const u32x4 xx = x[mm][bj], cc = c[mm][bj];
;                         const f32x4 c0 = (f32x4){bf_lo(cc.x), bf_hi(cc.x), bf_lo(cc.y), bf_hi(cc.y)}, c1 = (f32x4){bf_lo(cc.z), bf_hi(cc.z), bf_lo(cc.w), bf_hi(cc.w)};
;                         f32x4 v0 = acc[ai][bj][m][0] * rs[ai][m], v1 = acc[ai][bj][m][1] * rs[ai][m];
; #pragma unroll
;                         for (int e = 0; e < 4; ++e) { v0[e] = sigm(v0[e]) * c0[e]; v1[e] = sigm(v1[e]) * c1[e]; }
;                         const f32x4 x0 = (f32x4){bf_lo(xx.x), bf_hi(xx.x), bf_lo(xx.y), bf_hi(xx.y)} + v0, x1 = (f32x4){bf_lo(xx.z), bf_hi(xx.z), bf_lo(xx.w), bf_hi(xx.w)} + v1;
;                         sq += sumsq8(x0, x1); *(u32x4*)(E.xout16 + (size_t)row * D + col0 + bj * 128) = pack8(x0, x1); }
;                     sq += __shfl_xor(sq, 16); sq += __shfl_xor(sq, 32); if (fq == 0) sslot[row] = sq; }
	v_lshlrev_b32_e32 v166, 16, v150
	v_and_b32_e32 v167, 0xffff0000, v150
	v_lshlrev_b32_e32 v174, 16, v151
	v_add_f32_e32 v0, 1.0, v0
	v_rcp_f32_e32 v158, v0
	v_mul_f32_e32 v0, 0xbfb8aa3b, v164
	v_exp_f32_e32 v0, v0
	v_and_b32_e32 v175, 0xffff0000, v151
	v_lshlrev_b32_e32 v168, 16, v152
	v_and_b32_e32 v169, 0xffff0000, v152
	v_add_f32_e32 v0, 1.0, v0
	v_rcp_f32_e32 v164, v0
	v_mul_f32_e32 v0, 0xbfb8aa3b, v159
	v_exp_f32_e32 v0, v0
	v_lshlrev_b32_e32 v152, 16, v153
	v_and_b32_e32 v153, 0xffff0000, v153
	v_add_f32_e32 v0, 1.0, v0
	v_rcp_f32_e32 v159, v0
	v_mul_f32_e32 v0, 0xbfb8aa3b, v165
	v_exp_f32_e32 v0, v0
	s_nop 0
	v_add_f32_e32 v0, 1.0, v0
	v_rcp_f32_e32 v165, v0
	v_mul_f32_e32 v0, 0xbfb8aa3b, v156
	v_exp_f32_e32 v0, v0
	s_nop 0
	v_add_f32_e32 v0, 1.0, v0
	v_rcp_f32_e32 v156, v0
	v_mul_f32_e32 v0, 0xbfb8aa3b, v160
	v_exp_f32_e32 v0, v0
	v_lshlrev_b32_e32 v160, 16, v146
	v_add_f32_e32 v0, 1.0, v0
	v_rcp_f32_e32 v150, v0
	v_mul_f32_e32 v0, 0xbfb8aa3b, v157
	v_exp_f32_e32 v0, v0
	s_nop 0
	v_add_f32_e32 v0, 1.0, v0
	v_rcp_f32_e32 v157, v0
	v_mul_f32_e32 v0, 0xbfb8aa3b, v161
	v_exp_f32_e32 v0, v0
	v_and_b32_e32 v161, 0xffff0000, v146
	v_lshlrev_b32_e32 v146, 16, v147
	v_and_b32_e32 v147, 0xffff0000, v147
	v_add_f32_e32 v0, 1.0, v0
	v_rcp_f32_e32 v151, v0
	v_pk_fma_f32 v[156:157], v[156:157], v[174:175], v[146:147]
	v_pk_fma_f32 v[146:147], v[158:159], v[166:167], v[160:161]
	v_lshlrev_b32_e32 v158, 16, v148
	v_and_b32_e32 v159, 0xffff0000, v148
	v_lshlrev_b32_e32 v148, 16, v149
	v_and_b32_e32 v149, 0xffff0000, v149
	v_pk_fma_f32 v[150:151], v[150:151], v[152:153], v[148:149]
	v_mul_f32_e32 v0, v147, v147
	v_mul_f32_e32 v152, v157, v157
	v_pk_fma_f32 v[148:149], v[164:165], v[168:169], v[158:159]
	v_fmac_f32_e32 v0, v146, v146
	v_fmac_f32_e32 v152, v156, v156
	v_add_f32_e32 v0, v0, v152
	v_mul_f32_e32 v152, v149, v149
	v_fmac_f32_e32 v152, v148, v148
	v_add_f32_e32 v0, v152, v0
	v_mul_f32_e32 v152, v151, v151
	v_fmac_f32_e32 v152, v150, v150
	v_add_f32_e32 v0, v152, v0
	v_add_f32_e32 v0, v176, v0
	v_cvt_pk_bf16_f32 v146, v146, v147
	v_cvt_pk_bf16_f32 v147, v156, v157
	v_cvt_pk_bf16_f32 v148, v148, v149
	v_cvt_pk_bf16_f32 v149, v150, v151
	s_waitcnt lgkmcnt(0)
	global_store_dwordx4 v[226:227], v[218:221], off
	v_lshl_add_u64 v[228:229], v[154:155], 0, v[230:231]
	ds_bpermute_b32 v222, v243, v146
	ds_bpermute_b32 v223, v243, v147
	ds_bpermute_b32 v224, v243, v148
	ds_bpermute_b32 v225, v243, v149
	ds_bpermute_b32 v146, v171, v0
	s_waitcnt lgkmcnt(0)
	v_add_f32_e32 v0, v0, v146
	ds_bpermute_b32 v146, v170, v0
	s_and_saveexec_b64 s[8:9], s[40:41]
	s_cbranch_execz .LBB0_323
	v_lshl_add_u64 v[148:149], v[210:211], 2, s[44:45]
	s_waitcnt lgkmcnt(0)
	v_add_f32_e32 v0, v0, v146
	global_store_dword v[148:149], v0, off offset:640
; __device__ __forceinline__ float bf_lo(unsigned w) { return __uint_as_float(w << 16); }
; __device__ __forceinline__ float bf_hi(unsigned w) { return __uint_as_float(w & 0xffff0000u); }
; __device__ __forceinline__ float sigm(float v) { return __builtin_amdgcn_rcpf(1.0f + __builtin_amdgcn_exp2f(-1.44269504089f * v)); }
; __device__ __forceinline__ u32x4 pack8(const f32x4& v0, const f32x4& v1) { u32x4 w; w.x = cvt_pk_bf16(v0[0], v0[1]); w.y = cvt_pk_bf16(v0[2], v0[3]); w.z = cvt_pk_bf16(v1[0], v1[1]); w.w = cvt_pk_bf16(v1[2], v1[3]); return w; }
; __device__ __forceinline__ float sumsq8(const f32x4& v0, const f32x4& v1) { return (v0[0] * v0[0] + v0[1] * v0[1]) + (v0[2] * v0[2] + v0[3] * v0[3]) + (v1[0] * v1[0] + v1[1] * v1[1]) + (v1[2] * v1[2] + v1[3] * v1[3]); }
; __device__ __forceinline__ void epi_run(const Epi& E, f32x4 (&acc)[2][2][4][2], const Unit& u, int wr, int wc, int fr, int fq) {
;     ...
;                 for (int mm = 0; mm < 2; ++mm) { const int m = 2 * mh + mm, row = row0 + ai * 128 + m * 16; float sq = 0.f;
; #pragma unroll
;                     for (int bj = 0; bj < 2; ++bj) { const u32x4 xx = x[mm][bj], cc = c[mm][bj];
;                         const f32x4 c0 = (f32x4){bf_lo(cc.x), bf_hi(cc.x), bf_lo(cc.y), bf_hi(cc.y)}, c1 = (f32x4){bf_lo(cc.z), bf_hi(cc.z), bf_lo(cc.w), bf_hi(cc.w)};
;                         f32x4 v0 = acc[ai][bj][m][0] * rs[ai][m], v1 = acc[ai][bj][m][1] * rs[ai][m];
; #pragma unroll
;                         for (int e = 0; e < 4; ++e) { v0[e] = sigm(v0[e]) * c0[e]; v1[e] = sigm(v1[e]) * c1[e]; }
;                         const f32x4 x0 = (f32x4){bf_lo(xx.x), bf_hi(xx.x), bf_lo(xx.y), bf_hi(xx.y)} + v0, x1 = (f32x4){bf_lo(xx.z), bf_hi(xx.z), bf_lo(xx.w), bf_hi(xx.w)} + v1;
;                         sq += sumsq8(x0, x1); *(u32x4*)(E.xout16 + (size_t)row * D + col0 + bj * 128) = pack8(x0, x1); }
;                     sq += __shfl_xor(sq, 16); sq += __shfl_xor(sq, 32); if (fq == 0) sslot[row] = sq; }
.LBB0_323:
	s_or_b64 exec, exec, s[8:9]
	v_add_f32_e32 v0, v172, v173
	v_fmamk_f32 v0, v0, 0x3a800000, v197
	v_rsq_f32_e32 v0, v0
	s_waitcnt vmcnt(3)
	v_lshlrev_b32_e32 v156, 16, v142
	v_and_b32_e32 v157, 0xffff0000, v142
	v_lshlrev_b32_e32 v158, 16, v144
	v_pk_mul_f32 v[154:155], v[10:11], v[0:1] op_sel_hi:[1,0]
	v_pk_mul_f32 v[148:149], v[16:17], v[0:1] op_sel_hi:[1,0]
	v_mul_f32_e32 v155, 0xbfb8aa3b, v155
	v_exp_f32_e32 v155, v155
	v_mul_f32_e32 v148, 0xbfb8aa3b, v148
	v_exp_f32_e32 v148, v148
	v_pk_mul_f32 v[152:153], v[12:13], v[0:1] op_sel_hi:[1,0]
	v_add_f32_e32 v142, 1.0, v155
	v_rcp_f32_e32 v155, v142
	v_and_b32_e32 v159, 0xffff0000, v144
	v_add_f32_e32 v142, 1.0, v148
	v_mul_f32_e32 v144, 0xbfb8aa3b, v152
	v_mul_f32_e32 v148, 0xbfb8aa3b, v149
	v_exp_f32_e32 v144, v144
	v_exp_f32_e32 v149, v148
	v_pk_mul_f32 v[150:151], v[14:15], v[0:1] op_sel_hi:[1,0]
	v_rcp_f32_e32 v148, v142
	v_mul_f32_e32 v150, 0xbfb8aa3b, v150
	v_mul_f32_e32 v151, 0xbfb8aa3b, v151
	v_exp_f32_e32 v150, v150
	v_exp_f32_e32 v151, v151
	v_add_f32_e32 v142, 1.0, v144
	v_add_f32_e32 v144, 1.0, v149
	v_mul_f32_e32 v149, 0xbfb8aa3b, v153
	v_mul_f32_e32 v154, 0xbfb8aa3b, v154
	v_exp_f32_e32 v160, v149
	v_exp_f32_e32 v154, v154
	v_add_f32_e32 v150, 1.0, v150
	v_add_f32_e32 v151, 1.0, v151
	v_rcp_f32_e32 v150, v150
	v_rcp_f32_e32 v151, v151
	v_rcp_f32_e32 v149, v144
	v_lshlrev_b32_e32 v152, 16, v143
	v_and_b32_e32 v153, 0xffff0000, v143
	v_add_f32_e32 v143, 1.0, v160
	v_add_f32_e32 v154, 1.0, v154
	v_rcp_f32_e32 v142, v142
	v_rcp_f32_e32 v143, v143
	v_rcp_f32_e32 v154, v154
	v_lshlrev_b32_e32 v160, 16, v138
	v_and_b32_e32 v161, 0xffff0000, v138
	v_lshlrev_b32_e32 v138, 16, v139
	v_and_b32_e32 v139, 0xffff0000, v139
	v_lshlrev_b32_e32 v144, 16, v145
	v_and_b32_e32 v145, 0xffff0000, v145
	v_pk_fma_f32 v[148:149], v[148:149], v[152:153], v[138:139]
	v_pk_fma_f32 v[138:139], v[150:151], v[156:157], v[160:161]
	v_lshlrev_b32_e32 v150, 16, v140
	v_and_b32_e32 v151, 0xffff0000, v140
	v_lshlrev_b32_e32 v140, 16, v141
	v_and_b32_e32 v141, 0xffff0000, v141
	v_pk_fma_f32 v[142:143], v[142:143], v[144:145], v[140:141]
	v_mul_f32_e32 v144, v139, v139
	v_mul_f32_e32 v145, v149, v149
	v_pk_fma_f32 v[140:141], v[154:155], v[158:159], v[150:151]
	v_fmac_f32_e32 v144, v138, v138
	v_fmac_f32_e32 v145, v148, v148
	v_add_f32_e32 v144, v144, v145
	v_mul_f32_e32 v145, v141, v141
	v_fmac_f32_e32 v145, v140, v140
	v_add_f32_e32 v144, v145, v144
	v_mul_f32_e32 v145, v143, v143
	v_fmac_f32_e32 v145, v142, v142
	v_cvt_pk_bf16_f32 v140, v140, v141
	v_cvt_pk_bf16_f32 v141, v142, v143
	v_pk_mul_f32 v[142:143], v[6:7], v[0:1] op_sel_hi:[1,0]
	v_pk_mul_f32 v[150:151], v[2:3], v[0:1] op_sel_hi:[1,0]
	v_mul_f32_e32 v142, 0xbfb8aa3b, v142
	v_exp_f32_e32 v142, v142
	v_add_f32_e32 v158, v145, v144
	v_cvt_pk_bf16_f32 v138, v138, v139
	v_cvt_pk_bf16_f32 v139, v148, v149
	v_pk_mul_f32 v[144:145], v[8:9], v[0:1] op_sel_hi:[1,0]
	v_pk_mul_f32 v[148:149], v[4:5], v[0:1] op_sel_hi:[1,0]
	v_add_f32_e32 v0, 1.0, v142
	v_mul_f32_e32 v142, 0xbfb8aa3b, v150
	v_exp_f32_e32 v150, v142
	v_mul_f32_e32 v142, 0xbfb8aa3b, v143
	v_exp_f32_e32 v143, v142
	v_rcp_f32_e32 v142, v0
	v_add_f32_e32 v0, 1.0, v150
	v_rcp_f32_e32 v150, v0
	v_add_f32_e32 v0, 1.0, v143
	v_mul_f32_e32 v143, 0xbfb8aa3b, v151
	v_exp_f32_e32 v151, v143
	s_waitcnt vmcnt(1)
	v_lshlrev_b32_e32 v152, 16, v134
	v_and_b32_e32 v153, 0xffff0000, v134
	v_mul_f32_e32 v134, 0xbfb8aa3b, v144
	v_exp_f32_e32 v134, v134
	v_rcp_f32_e32 v143, v0
	v_add_f32_e32 v0, 1.0, v151
	v_rcp_f32_e32 v151, v0
	v_add_f32_e32 v0, 1.0, v134
	v_mul_f32_e32 v134, 0xbfb8aa3b, v148
	v_lshlrev_b32_e32 v154, 16, v136
	v_and_b32_e32 v155, 0xffff0000, v136
	v_exp_f32_e32 v134, v134
	v_mul_f32_e32 v136, 0xbfb8aa3b, v145
	v_exp_f32_e32 v136, v136
	v_rcp_f32_e32 v144, v0
	v_add_f32_e32 v0, 1.0, v134
	v_rcp_f32_e32 v134, v0
	v_add_f32_e32 v0, 1.0, v136
	v_mul_f32_e32 v136, 0xbfb8aa3b, v149
	v_exp_f32_e32 v136, v136
	v_rcp_f32_e32 v145, v0
	v_lshlrev_b32_e32 v148, 16, v135
	v_and_b32_e32 v149, 0xffff0000, v135
	v_add_f32_e32 v0, 1.0, v136
	v_rcp_f32_e32 v135, v0
	v_lshlrev_b32_e32 v156, 16, v130
	v_and_b32_e32 v157, 0xffff0000, v130
	v_lshlrev_b32_e32 v130, 16, v131
	v_and_b32_e32 v131, 0xffff0000, v131
	v_lshlrev_b32_e32 v136, 16, v137
	v_and_b32_e32 v137, 0xffff0000, v137
	v_pk_fma_f32 v[144:145], v[144:145], v[148:149], v[130:131]
	v_pk_fma_f32 v[130:131], v[142:143], v[152:153], v[156:157]
	v_lshlrev_b32_e32 v142, 16, v132
	v_and_b32_e32 v143, 0xffff0000, v132
	v_lshlrev_b32_e32 v132, 16, v133
	v_and_b32_e32 v133, 0xffff0000, v133
	v_pk_fma_f32 v[136:137], v[134:135], v[136:137], v[132:133]
	v_mul_f32_e32 v0, v131, v131
	v_mul_f32_e32 v132, v145, v145
	v_pk_fma_f32 v[134:135], v[150:151], v[154:155], v[142:143]
	v_fmac_f32_e32 v0, v130, v130
	v_fmac_f32_e32 v132, v144, v144
	v_add_f32_e32 v0, v0, v132
	v_mul_f32_e32 v132, v135, v135
	v_fmac_f32_e32 v132, v134, v134
	v_add_f32_e32 v0, v132, v0
	v_mul_f32_e32 v132, v137, v137
	v_fmac_f32_e32 v132, v136, v136
	v_add_f32_e32 v0, v132, v0
	v_add_f32_e32 v0, v158, v0
	ds_bpermute_b32 v148, v171, v0
	s_waitcnt lgkmcnt(1)
	v_lshlrev_b64 v[146:147], 11, v[162:163]
	v_lshl_add_u64 v[132:133], s[78:79], 0, v[146:147]
	v_lshl_add_u64 v[142:143], v[212:213], 1, v[132:133]
	v_cvt_pk_bf16_f32 v132, v130, v131
	s_waitcnt lgkmcnt(0)
	v_add_f32_e32 v0, v0, v148
	ds_bpermute_b32 v130, v170, v0
	v_cvt_pk_bf16_f32 v133, v144, v145
	v_cvt_pk_bf16_f32 v134, v134, v135
	v_cvt_pk_bf16_f32 v135, v136, v137
	s_waitcnt lgkmcnt(0)
	global_store_dwordx4 v[228:229], v[222:225], off offset:256
	v_lshl_add_u64 v[226:227], v[142:143], 0, v[230:231]
	ds_bpermute_b32 v218, v243, v138
	ds_bpermute_b32 v219, v243, v139
	ds_bpermute_b32 v220, v243, v140
	ds_bpermute_b32 v221, v243, v141
	s_waitcnt lgkmcnt(0)
	global_store_dwordx4 v[226:227], v[218:221], off
	v_lshl_add_u64 v[228:229], v[142:143], 0, v[230:231]
	ds_bpermute_b32 v222, v243, v132
	ds_bpermute_b32 v223, v243, v133
	ds_bpermute_b32 v224, v243, v134
	ds_bpermute_b32 v225, v243, v135
	s_waitcnt lgkmcnt(0)
	global_store_dwordx4 v[228:229], v[222:225], off offset:256
	s_and_saveexec_b64 s[8:9], s[40:41]
	s_cbranch_execz .LBB0_325
	v_lshl_add_u64 v[132:133], v[210:211], 2, s[44:45]
	s_waitcnt lgkmcnt(0)
	v_add_f32_e32 v0, v0, v130
	global_store_dword v[132:133], v0, off offset:704
